# LN load hoisting extended to P11 and layer>0 P0 (mod, gain/bias, split-K partial loads issued up front)
# speedup vs baseline: 1.0099x; 1.0055x over previous
; __device__ __forceinline__ float* xrow(const Frame& F, int m) { return m < ML ? (float*)(F.out + (size_t)m * D) : WSP(float, WS_XC) + (size_t)(m - ML) * D; }
;     ...
;         float* xr = xrow(F, m);
;         const float* xs = (m < ML) ? (src_l ? src_l + (size_t)m * D : xr) : (src_c ? src_c + (size_t)(m - ML) * D : xr);
;         f32x4 v[8];
; #pragma unroll
;         for (int j = 0; j < 8; ++j) v[j] = ((const f32x4*)xs)[F.lane + 64 * j];
;         if (POST && part != nullptr && m >= ML) {
;             const v2u* pp = (const v2u*)(part + (size_t)(m - ML) * D);
; #pragma unroll
;             for (int j = 0; j < 8; ++j) { const int o = F.lane + 64 * j; const v2u p0 = pp[o], p1 = pp[o + (size_t)MC * D / 4], p2 = pp[o + 2 * ((size_t)MC * D / 4)], p3 = pp[o + 3 * ((size_t)MC * D / 4)];
;                 const f32x4 ps = ((f32x4){bflo(p0.x), bfhi(p0.x), bflo(p0.y), bfhi(p0.y)} + (f32x4){bflo(p1.x), bfhi(p1.x), bflo(p1.y), bfhi(p1.y)}) + ((f32x4){bflo(p2.x), bfhi(p2.x), bflo(p2.y), bfhi(p2.y)} + (f32x4){bflo(p3.x), bfhi(p3.x), bflo(p3.y), bfhi(p3.y)});
;                 v[j] = v[j] * ALPHA + ((const f32x4*)pmod)[o] * pcoef * ps; }
.LBB0_76:
	s_add_i32 s66, s26, 0xffffc000
	s_cmpk_lt_i32 s26, 0x4000
	s_cselect_b64 s[28:29], -1, 0
	s_and_b64 s[4:5], s[28:29], exec
	s_cselect_b32 s5, s27, 0
	s_cselect_b32 s4, s26, s66
	s_cselect_b32 s15, s17, s37
	s_cselect_b32 s23, s16, s33
	s_lshl_b64 s[4:5], s[4:5], 13
	s_add_u32 s4, s23, s4
	s_addc_u32 s5, s15, s5
	v_lshl_add_u64 v[56:57], v[0:1], 4, s[4:5]
	v_add_co_u32_e32 v4, vcc, 0x1000, v56
	global_load_dwordx4 v[28:31], v[56:57], off
	global_load_dwordx4 v[32:35], v[56:57], off offset:1024
	global_load_dwordx4 v[24:27], v[56:57], off offset:2048
	global_load_dwordx4 v[20:23], v[56:57], off offset:3072
	v_addc_co_u32_e32 v5, vcc, 0, v57, vcc
	global_load_dwordx4 v[16:19], v[4:5], off
	global_load_dwordx4 v[12:15], v[4:5], off offset:1024
	global_load_dwordx4 v[8:11], v[4:5], off offset:2048
	s_nop 0
	global_load_dwordx4 v[4:7], v[4:5], off offset:3072
	s_cmpk_gt_i32 s26, 0x3fff
	s_cselect_b64 s[30:31], -1, 0
	s_and_b64 s[4:5], s[20:21], s[30:31]
	s_andn2_b64 vcc, exec, s[4:5]
	s_cbranch_vccnz .LBB0_78
	s_lshl_b64 s[4:5], s[66:67], 12
	v_lshl_add_u64 v[64:65], v[52:53], 0, s[4:5]
	v_add_co_u32_e32 v62, vcc, 0x800000, v64
	global_load_dwordx2 v[36:37], v[64:65], off
	s_nop 0
	v_addc_co_u32_e32 v63, vcc, 0, v65, vcc
	v_add_co_u32_e32 v60, vcc, 0x1000000, v64
	global_load_dwordx2 v[38:39], v[62:63], off
	s_nop 0
	v_addc_co_u32_e32 v61, vcc, 0, v65, vcc
	v_add_co_u32_e32 v58, vcc, 0x1800000, v64
	global_load_dwordx2 v[66:67], v[60:61], off
	s_nop 0
	v_addc_co_u32_e32 v59, vcc, 0, v65, vcc
	global_load_dwordx2 v[68:69], v[58:59], off
	global_load_dwordx4 v[104:107], v[50:51], off
	global_load_dwordx2 v[136:137], v[64:65], off offset:512
	global_load_dwordx2 v[138:139], v[62:63], off offset:512
	global_load_dwordx2 v[140:141], v[60:61], off offset:512
	global_load_dwordx2 v[142:143], v[58:59], off offset:512
	global_load_dwordx4 v[108:111], v[50:51], off offset:1024
	global_load_dwordx2 v[144:145], v[64:65], off offset:1024
	global_load_dwordx2 v[146:147], v[62:63], off offset:1024
	global_load_dwordx2 v[148:149], v[60:61], off offset:1024
	global_load_dwordx2 v[150:151], v[58:59], off offset:1024
	global_load_dwordx4 v[112:115], v[50:51], off offset:2048
	global_load_dwordx2 v[152:153], v[64:65], off offset:1536
	global_load_dwordx2 v[154:155], v[62:63], off offset:1536
	global_load_dwordx2 v[156:157], v[60:61], off offset:1536
	global_load_dwordx2 v[158:159], v[58:59], off offset:1536
	global_load_dwordx4 v[116:119], v[50:51], off offset:3072
	global_load_dwordx2 v[160:161], v[64:65], off offset:2048
	global_load_dwordx2 v[162:163], v[62:63], off offset:2048
	global_load_dwordx2 v[164:165], v[60:61], off offset:2048
	global_load_dwordx2 v[166:167], v[58:59], off offset:2048
	global_load_dwordx4 v[120:123], v[48:49], off offset:-4096
	global_load_dwordx2 v[168:169], v[64:65], off offset:2560
	global_load_dwordx2 v[170:171], v[62:63], off offset:2560
	global_load_dwordx2 v[172:173], v[60:61], off offset:2560
	global_load_dwordx2 v[174:175], v[58:59], off offset:2560
	global_load_dwordx4 v[124:127], v[48:49], off offset:-3072
	global_load_dwordx2 v[176:177], v[64:65], off offset:3072
	global_load_dwordx2 v[178:179], v[62:63], off offset:3072
	global_load_dwordx2 v[180:181], v[60:61], off offset:3072
	global_load_dwordx2 v[182:183], v[58:59], off offset:3072
	global_load_dwordx4 v[128:131], v[48:49], off offset:-2048
	global_load_dwordx2 v[184:185], v[64:65], off offset:3584
	global_load_dwordx2 v[186:187], v[62:63], off offset:3584
	global_load_dwordx2 v[188:189], v[60:61], off offset:3584
	global_load_dwordx2 v[190:191], v[58:59], off offset:3584
	global_load_dwordx4 v[132:135], v[48:49], off offset:-1024
	s_mov_b32 s4, 0x3fb504f3
	s_waitcnt vmcnt(36)
	v_lshlrev_b32_e32 v70, 16, v36
	v_and_b32_e32 v71, 0xffff0000, v36
	v_lshlrev_b32_e32 v36, 16, v37
	v_and_b32_e32 v37, 0xffff0000, v37
	v_lshlrev_b32_e32 v72, 16, v38
	v_and_b32_e32 v73, 0xffff0000, v38
	v_lshlrev_b32_e32 v38, 16, v39
	v_and_b32_e32 v39, 0xffff0000, v39
	v_pk_add_f32 v[70:71], v[70:71], v[72:73]
	v_pk_add_f32 v[36:37], v[36:37], v[38:39]
	v_lshlrev_b32_e32 v38, 16, v66
	v_and_b32_e32 v39, 0xffff0000, v66
	v_lshlrev_b32_e32 v66, 16, v67
	v_and_b32_e32 v67, 0xffff0000, v67
	v_lshlrev_b32_e32 v72, 16, v68
	v_and_b32_e32 v73, 0xffff0000, v68
	v_lshlrev_b32_e32 v68, 16, v69
	v_and_b32_e32 v69, 0xffff0000, v69
	v_pk_add_f32 v[38:39], v[38:39], v[72:73]
	v_pk_add_f32 v[66:67], v[66:67], v[68:69]
	v_pk_add_f32 v[68:69], v[70:71], v[38:39]
	v_pk_add_f32 v[66:67], v[36:37], v[66:67]
	s_nop 0
	s_waitcnt vmcnt(35)
	v_pk_mul_f32 v[38:39], v[106:107], 0.5 op_sel_hi:[1,0]
	v_pk_mul_f32 v[36:37], v[104:105], 0.5 op_sel_hi:[1,0]
	v_pk_mul_f32 v[38:39], v[38:39], v[66:67]
	v_pk_mul_f32 v[36:37], v[36:37], v[68:69]
	v_pk_fma_f32 v[30:31], v[30:31], s[4:5], v[38:39] op_sel_hi:[1,0,1]
	v_pk_fma_f32 v[28:29], v[28:29], s[4:5], v[36:37] op_sel_hi:[1,0,1]
	s_nop 0
	s_nop 0
	s_nop 0
	s_nop 0
	s_waitcnt vmcnt(34)
	v_lshlrev_b32_e32 v70, 16, v136
	v_and_b32_e32 v71, 0xffff0000, v136
	v_lshlrev_b32_e32 v36, 16, v137
	v_and_b32_e32 v37, 0xffff0000, v137
	s_waitcnt vmcnt(33)
	v_lshlrev_b32_e32 v72, 16, v138
	v_and_b32_e32 v73, 0xffff0000, v138
	v_lshlrev_b32_e32 v38, 16, v139
	v_and_b32_e32 v39, 0xffff0000, v139
	v_pk_add_f32 v[70:71], v[70:71], v[72:73]
	v_pk_add_f32 v[36:37], v[36:37], v[38:39]
	s_waitcnt vmcnt(32)
	v_lshlrev_b32_e32 v38, 16, v140
	v_and_b32_e32 v39, 0xffff0000, v140
	v_lshlrev_b32_e32 v66, 16, v141
	v_and_b32_e32 v67, 0xffff0000, v141
	s_waitcnt vmcnt(31)
;     ...
;         if (POST && part != nullptr && m >= ML) {
;             const v2u* pp = (const v2u*)(part + (size_t)(m - ML) * D);
; #pragma unroll
;             for (int j = 0; j < 8; ++j) { const int o = F.lane + 64 * j; const v2u p0 = pp[o], p1 = pp[o + (size_t)MC * D / 4], p2 = pp[o + 2 * ((size_t)MC * D / 4)], p3 = pp[o + 3 * ((size_t)MC * D / 4)];
;                 const f32x4 ps = ((f32x4){bflo(p0.x), bfhi(p0.x), bflo(p0.y), bfhi(p0.y)} + (f32x4){bflo(p1.x), bfhi(p1.x), bflo(p1.y), bfhi(p1.y)}) + ((f32x4){bflo(p2.x), bfhi(p2.x), bflo(p2.y), bfhi(p2.y)} + (f32x4){bflo(p3.x), bfhi(p3.x), bflo(p3.y), bfhi(p3.y)});
;                 v[j] = v[j] * ALPHA + ((const f32x4*)pmod)[o] * pcoef * ps; }
	v_lshlrev_b32_e32 v72, 16, v142
	v_and_b32_e32 v73, 0xffff0000, v142
	v_lshlrev_b32_e32 v68, 16, v143
	v_and_b32_e32 v69, 0xffff0000, v143
	v_pk_add_f32 v[38:39], v[38:39], v[72:73]
	v_pk_add_f32 v[66:67], v[66:67], v[68:69]
	v_pk_add_f32 v[68:69], v[70:71], v[38:39]
	v_pk_add_f32 v[66:67], v[36:37], v[66:67]
	s_nop 0
	s_waitcnt vmcnt(30)
	v_pk_mul_f32 v[38:39], v[110:111], 0.5 op_sel_hi:[1,0]
	v_pk_mul_f32 v[36:37], v[108:109], 0.5 op_sel_hi:[1,0]
	s_nop 0
	v_pk_mul_f32 v[68:69], v[36:37], v[68:69]
	v_pk_mul_f32 v[36:37], v[38:39], v[66:67]
	v_pk_fma_f32 v[38:39], v[32:33], s[4:5], v[68:69] op_sel_hi:[1,0,1]
	v_pk_fma_f32 v[36:37], v[34:35], s[4:5], v[36:37] op_sel_hi:[1,0,1]
	s_nop 0
	s_nop 0
	s_nop 0
	s_nop 0
	s_waitcnt vmcnt(29)
	v_lshlrev_b32_e32 v70, 16, v144
	v_and_b32_e32 v71, 0xffff0000, v144
	v_lshlrev_b32_e32 v32, 16, v145
	v_and_b32_e32 v33, 0xffff0000, v145
	s_waitcnt vmcnt(28)
	v_lshlrev_b32_e32 v72, 16, v146
	v_and_b32_e32 v73, 0xffff0000, v146
	v_lshlrev_b32_e32 v34, 16, v147
	v_and_b32_e32 v35, 0xffff0000, v147
	v_pk_add_f32 v[70:71], v[70:71], v[72:73]
	v_pk_add_f32 v[32:33], v[32:33], v[34:35]
	s_waitcnt vmcnt(27)
	v_lshlrev_b32_e32 v34, 16, v148
	v_and_b32_e32 v35, 0xffff0000, v148
	v_lshlrev_b32_e32 v66, 16, v149
	v_and_b32_e32 v67, 0xffff0000, v149
	s_waitcnt vmcnt(26)
	v_lshlrev_b32_e32 v72, 16, v150
	v_and_b32_e32 v73, 0xffff0000, v150
	v_lshlrev_b32_e32 v68, 16, v151
	v_and_b32_e32 v69, 0xffff0000, v151
	v_pk_add_f32 v[34:35], v[34:35], v[72:73]
	v_pk_add_f32 v[66:67], v[66:67], v[68:69]
	v_pk_add_f32 v[68:69], v[70:71], v[34:35]
	v_pk_add_f32 v[66:67], v[32:33], v[66:67]
	s_nop 0
	s_waitcnt vmcnt(25)
	v_pk_mul_f32 v[34:35], v[114:115], 0.5 op_sel_hi:[1,0]
	v_pk_mul_f32 v[32:33], v[112:113], 0.5 op_sel_hi:[1,0]
	v_pk_mul_f32 v[34:35], v[34:35], v[66:67]
	v_pk_mul_f32 v[32:33], v[32:33], v[68:69]
	v_pk_fma_f32 v[26:27], v[26:27], s[4:5], v[34:35] op_sel_hi:[1,0,1]
	v_pk_fma_f32 v[24:25], v[24:25], s[4:5], v[32:33] op_sel_hi:[1,0,1]
	s_nop 0
	s_nop 0
	s_nop 0
	s_nop 0
	s_waitcnt vmcnt(24)
	v_lshlrev_b32_e32 v70, 16, v152
	v_and_b32_e32 v71, 0xffff0000, v152
	v_lshlrev_b32_e32 v32, 16, v153
	v_and_b32_e32 v33, 0xffff0000, v153
	s_waitcnt vmcnt(23)
	v_lshlrev_b32_e32 v72, 16, v154
	v_and_b32_e32 v73, 0xffff0000, v154
	v_lshlrev_b32_e32 v34, 16, v155
	v_and_b32_e32 v35, 0xffff0000, v155
	v_pk_add_f32 v[70:71], v[70:71], v[72:73]
	v_pk_add_f32 v[32:33], v[32:33], v[34:35]
	s_waitcnt vmcnt(22)
	v_lshlrev_b32_e32 v34, 16, v156
	v_and_b32_e32 v35, 0xffff0000, v156
	v_lshlrev_b32_e32 v66, 16, v157
	v_and_b32_e32 v67, 0xffff0000, v157
	s_waitcnt vmcnt(21)
	v_lshlrev_b32_e32 v72, 16, v158
	v_and_b32_e32 v73, 0xffff0000, v158
	v_lshlrev_b32_e32 v68, 16, v159
	v_and_b32_e32 v69, 0xffff0000, v159
	v_pk_add_f32 v[34:35], v[34:35], v[72:73]
	v_pk_add_f32 v[66:67], v[66:67], v[68:69]
	v_pk_add_f32 v[68:69], v[70:71], v[34:35]
	v_pk_add_f32 v[66:67], v[32:33], v[66:67]
	s_nop 0
	s_waitcnt vmcnt(20)
	v_pk_mul_f32 v[34:35], v[118:119], 0.5 op_sel_hi:[1,0]
	v_pk_mul_f32 v[32:33], v[116:117], 0.5 op_sel_hi:[1,0]
	v_pk_mul_f32 v[34:35], v[34:35], v[66:67]
	v_pk_mul_f32 v[32:33], v[32:33], v[68:69]
	v_pk_fma_f32 v[22:23], v[22:23], s[4:5], v[34:35] op_sel_hi:[1,0,1]
	v_pk_fma_f32 v[20:21], v[20:21], s[4:5], v[32:33] op_sel_hi:[1,0,1]
	s_nop 0
	s_nop 0
	s_nop 0
	s_nop 0
	s_waitcnt vmcnt(19)
	v_lshlrev_b32_e32 v70, 16, v160
	v_and_b32_e32 v71, 0xffff0000, v160
	v_lshlrev_b32_e32 v32, 16, v161
	v_and_b32_e32 v33, 0xffff0000, v161
	s_waitcnt vmcnt(18)
	v_lshlrev_b32_e32 v72, 16, v162
	v_and_b32_e32 v73, 0xffff0000, v162
	v_lshlrev_b32_e32 v34, 16, v163
	v_and_b32_e32 v35, 0xffff0000, v163
	v_pk_add_f32 v[70:71], v[70:71], v[72:73]
	v_pk_add_f32 v[32:33], v[32:33], v[34:35]
	s_waitcnt vmcnt(17)
	v_lshlrev_b32_e32 v34, 16, v164
	v_and_b32_e32 v35, 0xffff0000, v164
	v_lshlrev_b32_e32 v66, 16, v165
	v_and_b32_e32 v67, 0xffff0000, v165
	s_waitcnt vmcnt(16)
	v_lshlrev_b32_e32 v72, 16, v166
	v_and_b32_e32 v73, 0xffff0000, v166
	v_lshlrev_b32_e32 v68, 16, v167
	v_and_b32_e32 v69, 0xffff0000, v167
	v_pk_add_f32 v[34:35], v[34:35], v[72:73]
	v_pk_add_f32 v[66:67], v[66:67], v[68:69]
	v_pk_add_f32 v[68:69], v[70:71], v[34:35]
	v_pk_add_f32 v[66:67], v[32:33], v[66:67]
	s_nop 0
	s_waitcnt vmcnt(15)
;     ...
;         if (POST && part != nullptr && m >= ML) {
;             const v2u* pp = (const v2u*)(part + (size_t)(m - ML) * D);
; #pragma unroll
;             for (int j = 0; j < 8; ++j) { const int o = F.lane + 64 * j; const v2u p0 = pp[o], p1 = pp[o + (size_t)MC * D / 4], p2 = pp[o + 2 * ((size_t)MC * D / 4)], p3 = pp[o + 3 * ((size_t)MC * D / 4)];
;                 const f32x4 ps = ((f32x4){bflo(p0.x), bfhi(p0.x), bflo(p0.y), bfhi(p0.y)} + (f32x4){bflo(p1.x), bfhi(p1.x), bflo(p1.y), bfhi(p1.y)}) + ((f32x4){bflo(p2.x), bfhi(p2.x), bflo(p2.y), bfhi(p2.y)} + (f32x4){bflo(p3.x), bfhi(p3.x), bflo(p3.y), bfhi(p3.y)});
;                 v[j] = v[j] * ALPHA + ((const f32x4*)pmod)[o] * pcoef * ps; }
	v_pk_mul_f32 v[34:35], v[122:123], 0.5 op_sel_hi:[1,0]
	v_pk_mul_f32 v[32:33], v[120:121], 0.5 op_sel_hi:[1,0]
	v_pk_mul_f32 v[34:35], v[34:35], v[66:67]
	v_pk_mul_f32 v[32:33], v[32:33], v[68:69]
	v_pk_fma_f32 v[18:19], v[18:19], s[4:5], v[34:35] op_sel_hi:[1,0,1]
	v_pk_fma_f32 v[16:17], v[16:17], s[4:5], v[32:33] op_sel_hi:[1,0,1]
	s_nop 0
	s_nop 0
	s_nop 0
	s_nop 0
	s_waitcnt vmcnt(14)
	v_lshlrev_b32_e32 v70, 16, v168
	v_and_b32_e32 v71, 0xffff0000, v168
	v_lshlrev_b32_e32 v32, 16, v169
	v_and_b32_e32 v33, 0xffff0000, v169
	s_waitcnt vmcnt(13)
	v_lshlrev_b32_e32 v72, 16, v170
	v_and_b32_e32 v73, 0xffff0000, v170
	v_lshlrev_b32_e32 v34, 16, v171
	v_and_b32_e32 v35, 0xffff0000, v171
	v_pk_add_f32 v[70:71], v[70:71], v[72:73]
	v_pk_add_f32 v[32:33], v[32:33], v[34:35]
	s_waitcnt vmcnt(12)
	v_lshlrev_b32_e32 v34, 16, v172
	v_and_b32_e32 v35, 0xffff0000, v172
	v_lshlrev_b32_e32 v66, 16, v173
	v_and_b32_e32 v67, 0xffff0000, v173
	s_waitcnt vmcnt(11)
	v_lshlrev_b32_e32 v72, 16, v174
	v_and_b32_e32 v73, 0xffff0000, v174
	v_lshlrev_b32_e32 v68, 16, v175
	v_and_b32_e32 v69, 0xffff0000, v175
	v_pk_add_f32 v[34:35], v[34:35], v[72:73]
	v_pk_add_f32 v[66:67], v[66:67], v[68:69]
	v_pk_add_f32 v[68:69], v[70:71], v[34:35]
	v_pk_add_f32 v[66:67], v[32:33], v[66:67]
	s_nop 0
	s_waitcnt vmcnt(10)
	v_pk_mul_f32 v[34:35], v[126:127], 0.5 op_sel_hi:[1,0]
	v_pk_mul_f32 v[32:33], v[124:125], 0.5 op_sel_hi:[1,0]
	v_pk_mul_f32 v[34:35], v[34:35], v[66:67]
	v_pk_mul_f32 v[32:33], v[32:33], v[68:69]
	v_pk_fma_f32 v[14:15], v[14:15], s[4:5], v[34:35] op_sel_hi:[1,0,1]
	v_pk_fma_f32 v[12:13], v[12:13], s[4:5], v[32:33] op_sel_hi:[1,0,1]
	s_nop 0
	s_nop 0
	s_nop 0
	s_nop 0
	s_waitcnt vmcnt(9)
	v_lshlrev_b32_e32 v70, 16, v176
	v_and_b32_e32 v71, 0xffff0000, v176
	v_lshlrev_b32_e32 v32, 16, v177
	v_and_b32_e32 v33, 0xffff0000, v177
	s_waitcnt vmcnt(8)
	v_lshlrev_b32_e32 v72, 16, v178
	v_and_b32_e32 v73, 0xffff0000, v178
	v_lshlrev_b32_e32 v34, 16, v179
	v_and_b32_e32 v35, 0xffff0000, v179
	v_pk_add_f32 v[70:71], v[70:71], v[72:73]
	v_pk_add_f32 v[32:33], v[32:33], v[34:35]
	s_waitcnt vmcnt(7)
	v_lshlrev_b32_e32 v34, 16, v180
	v_and_b32_e32 v35, 0xffff0000, v180
	v_lshlrev_b32_e32 v66, 16, v181
	v_and_b32_e32 v67, 0xffff0000, v181
	s_waitcnt vmcnt(6)
	v_lshlrev_b32_e32 v72, 16, v182
	v_and_b32_e32 v73, 0xffff0000, v182
	v_lshlrev_b32_e32 v68, 16, v183
	v_and_b32_e32 v69, 0xffff0000, v183
	v_pk_add_f32 v[34:35], v[34:35], v[72:73]
	v_pk_add_f32 v[66:67], v[66:67], v[68:69]
	v_pk_add_f32 v[68:69], v[70:71], v[34:35]
	v_pk_add_f32 v[66:67], v[32:33], v[66:67]
	s_nop 0
	s_waitcnt vmcnt(5)
	v_pk_mul_f32 v[34:35], v[130:131], 0.5 op_sel_hi:[1,0]
	v_pk_mul_f32 v[32:33], v[128:129], 0.5 op_sel_hi:[1,0]
	v_pk_mul_f32 v[34:35], v[34:35], v[66:67]
	v_pk_mul_f32 v[32:33], v[32:33], v[68:69]
	v_pk_fma_f32 v[10:11], v[10:11], s[4:5], v[34:35] op_sel_hi:[1,0,1]
	v_pk_fma_f32 v[8:9], v[8:9], s[4:5], v[32:33] op_sel_hi:[1,0,1]
	s_nop 0
	s_nop 0
	s_nop 0
	s_nop 0
	s_nop 0
	s_nop 0
	v_mov_b32_e32 v67, v30
	v_mov_b32_e32 v66, v36
	v_mov_b32_e32 v30, v37
	s_waitcnt vmcnt(4)
	v_lshlrev_b32_e32 v62, 16, v184
	v_and_b32_e32 v63, 0xffff0000, v184
	v_lshlrev_b32_e32 v32, 16, v185
	v_and_b32_e32 v33, 0xffff0000, v185
	s_waitcnt vmcnt(3)
	v_lshlrev_b32_e32 v64, 16, v186
	v_and_b32_e32 v65, 0xffff0000, v186
	v_lshlrev_b32_e32 v34, 16, v187
	v_and_b32_e32 v35, 0xffff0000, v187
	v_pk_add_f32 v[62:63], v[62:63], v[64:65]
	v_pk_add_f32 v[32:33], v[32:33], v[34:35]
	s_waitcnt vmcnt(2)
	v_lshlrev_b32_e32 v34, 16, v188
	v_and_b32_e32 v35, 0xffff0000, v188
	v_lshlrev_b32_e32 v60, 16, v189
	v_and_b32_e32 v61, 0xffff0000, v189
	s_waitcnt vmcnt(1)
	v_lshlrev_b32_e32 v64, 16, v190
	v_and_b32_e32 v65, 0xffff0000, v190
	v_lshlrev_b32_e32 v58, 16, v191
	v_and_b32_e32 v59, 0xffff0000, v191
	v_pk_add_f32 v[34:35], v[34:35], v[64:65]
	v_pk_add_f32 v[58:59], v[60:61], v[58:59]
	v_pk_add_f32 v[60:61], v[62:63], v[34:35]
	v_pk_add_f32 v[58:59], v[32:33], v[58:59]
	s_nop 0
	v_mov_b32_e32 v65, v28
	v_mov_b32_e32 v64, v38
	v_mov_b32_e32 v28, v39
	s_waitcnt vmcnt(0)
	v_pk_mul_f32 v[34:35], v[134:135], 0.5 op_sel_hi:[1,0]
	v_pk_mul_f32 v[32:33], v[132:133], 0.5 op_sel_hi:[1,0]
	v_pk_mul_f32 v[34:35], v[34:35], v[58:59]
	v_pk_mul_f32 v[32:33], v[32:33], v[60:61]
	v_pk_fma_f32 v[6:7], v[6:7], s[4:5], v[34:35] op_sel_hi:[1,0,1]
	v_pk_fma_f32 v[4:5], v[4:5], s[4:5], v[32:33] op_sel_hi:[1,0,1]
	s_branch .LBB0_79

;     ...
;         if (POST) {
;             float s = 0.f;
; #pragma unroll
;             for (int j = 0; j < 8; ++j) s += (v[j].x + v[j].y) + (v[j].z + v[j].w);
;             const float mean = wave_sum(s) * (1.f / D); float s2 = 0.f;
; #pragma unroll
;             for (int j = 0; j < 8; ++j) { v[j] = v[j] - mean; s2 += (v[j].x * v[j].x + v[j].y * v[j].y) + (v[j].z * v[j].z + v[j].w * v[j].w); }
;             const float rstd = 1.f / sqrtf(wave_sum(s2) * (1.f / D) + LN_EPS);
; #pragma unroll
;             for (int j = 0; j < 8; ++j) { const f32x4 gg = ((const f32x4*)g)[F.lane + 64 * j], bb = ((const f32x4*)b)[F.lane + 64 * j]; v[j] = v[j] * rstd * gg + bb; if (WX || m >= ML) ((f32x4*)xr)[F.lane + 64 * j] = v[j]; }
.LBB0_79:
	v_pk_add_f32 v[38:39], v[64:65], v[28:29]
	v_pk_add_f32 v[68:69], v[66:67], v[30:31]
	v_mov_b32_e32 v36, v25
	v_pk_add_f32 v[38:39], v[38:39], v[68:69]
	v_mov_b32_e32 v37, v26
	v_mov_b32_e32 v25, v27
	v_add_f32_e32 v3, 0, v39
	v_add_f32_e32 v63, v38, v3
	v_pk_add_f32 v[38:39], v[36:37], v[24:25]
	v_mov_b32_e32 v60, v17
	v_pk_add_f32 v[38:39], v[38:39], v[38:39] op_sel_hi:[0,1]
	v_mov_b32_e32 v62, v19
	v_add_f32_e32 v17, v20, v21
	v_add_f32_e32 v61, v22, v23
	v_mov_b32_e32 v19, v39
	v_mov_b32_e32 v58, v13
	v_mov_b32_e32 v59, v14
	v_mov_b32_e32 v13, v15
	v_pk_add_f32 v[68:69], v[16:17], v[60:61]
	v_pk_add_f32 v[38:39], v[18:19], v[62:63]
	v_mov_b32_e32 v32, v4
	v_pk_add_f32 v[38:39], v[68:69], v[38:39]
	v_pk_add_f32 v[68:69], v[58:59], v[12:13]
	v_pk_add_f32 v[38:39], v[38:39], v[38:39] op_sel_hi:[0,1]
	v_pk_add_f32 v[68:69], v[68:69], v[68:69] op_sel_hi:[0,1]
	v_mov_b32_e32 v34, v5
	v_mov_b32_e32 v14, v6
	v_mov_b32_e32 v26, v7
	v_add_f32_e32 v33, v8, v9
	v_add_f32_e32 v35, v10, v11
	v_mov_b32_e32 v15, v69
	v_mov_b32_e32 v27, v39
	v_pk_add_f32 v[32:33], v[32:33], v[34:35]
	v_pk_add_f32 v[14:15], v[14:15], v[26:27]
	s_nop 0
	v_pk_add_f32 v[14:15], v[32:33], v[14:15]
	global_load_dwordx4 v[32:35], v[42:43], off
	global_load_dwordx4 v[70:73], v[46:47], off
	global_load_dwordx4 v[160:163], v[42:43], off offset:1024
	global_load_dwordx4 v[164:167], v[46:47], off offset:1024
	global_load_dwordx4 v[168:171], v[42:43], off offset:2048
	global_load_dwordx4 v[172:175], v[46:47], off offset:2048
	global_load_dwordx4 v[176:179], v[42:43], off offset:3072
	global_load_dwordx4 v[180:183], v[46:47], off offset:3072
	global_load_dwordx4 v[184:187], v[40:41], off offset:-4096
	global_load_dwordx4 v[188:191], v[44:45], off offset:-4096
	global_load_dwordx4 v[196:199], v[40:41], off offset:-3072
	global_load_dwordx4 v[200:203], v[44:45], off offset:-3072
	global_load_dwordx4 v[204:207], v[40:41], off offset:-2048
	global_load_dwordx4 v[208:211], v[44:45], off offset:-2048
	global_load_dwordx4 v[212:215], v[40:41], off offset:-1024
	global_load_dwordx4 v[216:219], v[44:45], off offset:-1024
	v_add_f32_e32 v3, v14, v15
	v_mov_b32_e32 v14, v2
	s_nop 0
	v_add_f32_dpp v3, v3, v3 quad_perm:[1,0,3,2] row_mask:0xf bank_mask:0xf bound_ctrl:1
	s_nop 1
	v_add_f32_dpp v3, v3, v3 quad_perm:[2,3,0,1] row_mask:0xf bank_mask:0xf bound_ctrl:1
	s_nop 1
	v_add_f32_dpp v3, v3, v3 row_half_mirror row_mask:0xf bank_mask:0xf bound_ctrl:1
	s_nop 1
	v_add_f32_dpp v3, v3, v3 row_mirror row_mask:0xf bank_mask:0xf bound_ctrl:1
	s_nop 1
	v_mov_b32_dpp v14, v3 row_bcast:15 row_mask:0xa bank_mask:0xf
	v_add_f32_e32 v3, v3, v14
	v_mov_b32_e32 v14, v2
	s_nop 1
	v_mov_b32_dpp v14, v3 row_bcast:31 row_mask:0xc bank_mask:0xf
	v_add_f32_e32 v3, v3, v14
	s_nop 0
	v_readlane_b32 s15, v3, 63
	s_nop 1
	v_fmac_f32_e32 v31, s15, v224
	v_fmac_f32_e32 v29, s15, v224
	v_fmac_f32_e32 v67, s15, v224
	v_fmac_f32_e32 v65, s15, v224
	v_mul_f32_e32 v3, v29, v29
	v_mul_f32_e32 v14, v31, v31
	v_fmac_f32_e32 v3, v65, v65
	v_fmac_f32_e32 v14, v67, v67
	v_fmac_f32_e32 v30, s15, v224
	v_fmac_f32_e32 v28, s15, v224
	v_add_f32_e32 v3, v3, v14
	v_fmac_f32_e32 v66, s15, v224
	v_fmac_f32_e32 v64, s15, v224
	v_mul_f32_e32 v14, v28, v28
	v_mul_f32_e32 v15, v30, v30
	v_fmac_f32_e32 v14, v64, v64
	v_fmac_f32_e32 v15, v66, v66
	v_add_f32_e32 v14, v14, v15
	v_fmac_f32_e32 v25, s15, v224
	v_fmac_f32_e32 v36, s15, v224
	v_add_f32_e32 v3, v3, v14
	v_fmac_f32_e32 v37, s15, v224
	v_fmac_f32_e32 v24, s15, v224
	v_mul_f32_e32 v14, v36, v36
	v_mul_f32_e32 v15, v25, v25
	v_fmac_f32_e32 v14, v24, v24
	v_fmac_f32_e32 v15, v37, v37
	v_add_f32_e32 v14, v14, v15
	v_fmac_f32_e32 v23, s15, v224
	v_fmac_f32_e32 v21, s15, v224
	v_add_f32_e32 v3, v14, v3
	v_fmac_f32_e32 v22, s15, v224
	v_fmac_f32_e32 v20, s15, v224
	v_mul_f32_e32 v14, v21, v21
	v_mul_f32_e32 v15, v23, v23
	v_fmac_f32_e32 v14, v20, v20
	v_fmac_f32_e32 v15, v22, v22
	v_add_f32_e32 v14, v14, v15
	v_fmac_f32_e32 v62, s15, v224
	v_fmac_f32_e32 v60, s15, v224
	v_add_f32_e32 v3, v14, v3
	v_fmac_f32_e32 v18, s15, v224
	v_fmac_f32_e32 v16, s15, v224
	v_mul_f32_e32 v14, v60, v60
	v_mul_f32_e32 v15, v62, v62
	v_fmac_f32_e32 v14, v16, v16
	v_fmac_f32_e32 v15, v18, v18
	v_add_f32_e32 v14, v14, v15
	v_fmac_f32_e32 v13, s15, v224
	v_fmac_f32_e32 v58, s15, v224
	v_add_f32_e32 v3, v14, v3
	v_fmac_f32_e32 v59, s15, v224
	v_fmac_f32_e32 v12, s15, v224
	v_mul_f32_e32 v14, v58, v58
	v_mul_f32_e32 v15, v13, v13
	v_fmac_f32_e32 v14, v12, v12
	v_fmac_f32_e32 v15, v59, v59
	v_add_f32_e32 v14, v14, v15
	v_fmac_f32_e32 v11, s15, v224
	v_fmac_f32_e32 v9, s15, v224
	v_add_f32_e32 v3, v14, v3
	v_fmac_f32_e32 v10, s15, v224
	v_fmac_f32_e32 v8, s15, v224
	v_mul_f32_e32 v14, v9, v9
	v_mul_f32_e32 v15, v11, v11
	v_fmac_f32_e32 v14, v8, v8
	v_fmac_f32_e32 v15, v10, v10
	v_add_f32_e32 v14, v14, v15
	v_fma_f32 v7, s15, v224, v7
	v_fma_f32 v5, s15, v224, v5
	v_add_f32_e32 v3, v14, v3
	v_fma_f32 v6, s15, v224, v6
	v_fmac_f32_e32 v4, s15, v224
	v_mul_f32_e32 v14, v5, v5
	v_mul_f32_e32 v15, v7, v7
	v_fmac_f32_e32 v14, v4, v4
	v_fmac_f32_e32 v15, v6, v6
	v_add_f32_e32 v14, v14, v15
	v_add_f32_e32 v3, v14, v3
	v_mov_b32_e32 v14, v2
	v_mov_b32_e32 v27, v31
	v_add_f32_dpp v3, v3, v3 quad_perm:[1,0,3,2] row_mask:0xf bank_mask:0xf bound_ctrl:1
	s_nop 1
	v_add_f32_dpp v3, v3, v3 quad_perm:[2,3,0,1] row_mask:0xf bank_mask:0xf bound_ctrl:1
	s_nop 1
	v_add_f32_dpp v3, v3, v3 row_half_mirror row_mask:0xf bank_mask:0xf bound_ctrl:1
	s_nop 1
	v_add_f32_dpp v3, v3, v3 row_mirror row_mask:0xf bank_mask:0xf bound_ctrl:1
	s_nop 1
	v_mov_b32_dpp v14, v3 row_bcast:15 row_mask:0xa bank_mask:0xf
	v_add_f32_e32 v3, v3, v14
	v_mov_b32_e32 v14, v2
	s_nop 1
	v_mov_b32_dpp v14, v3 row_bcast:31 row_mask:0xc bank_mask:0xf
	v_add_f32_e32 v3, v3, v14
	s_nop 0
	v_readlane_b32 s4, v3, 63
	s_nop 1
	v_fma_f32 v3, s4, v226, v225
	v_mul_f32_e32 v14, 0x4f800000, v3
	v_cmp_gt_f32_e32 vcc, s73, v3
	s_nop 1
	v_cndmask_b32_e32 v3, v3, v14, vcc
	v_sqrt_f32_e32 v14, v3
	s_nop 0
	v_add_u32_e32 v15, -1, v14
	v_fma_f32 v17, -v15, v14, v3
	v_cmp_ge_f32_e64 s[4:5], 0, v17
	v_add_u32_e32 v17, 1, v14
	s_nop 0
	v_cndmask_b32_e64 v15, v14, v15, s[4:5]
	v_fma_f32 v14, -v17, v14, v3
	v_cmp_lt_f32_e64 s[4:5], 0, v14
	s_nop 1
	v_cndmask_b32_e64 v14, v15, v17, s[4:5]
	v_mul_f32_e32 v15, 0x37800000, v14
	v_cndmask_b32_e32 v14, v14, v15, vcc
	v_cmp_class_f32_e32 vcc, v3, v227
	s_nop 1
	v_cndmask_b32_e32 v3, v14, v3, vcc
	v_div_scale_f32 v14, s[4:5], v3, v3, 1.0
	v_rcp_f32_e32 v15, v14
	s_nop 0
	v_fma_f32 v17, -v14, v15, 1.0
	v_fmac_f32_e32 v15, v17, v15
	v_div_scale_f32 v17, vcc, 1.0, v3, 1.0
	v_mul_f32_e32 v19, v17, v15
	v_fma_f32 v26, -v14, v19, v17
	v_fmac_f32_e32 v19, v26, v15
	v_fma_f32 v14, -v14, v19, v17
	v_div_fmas_f32 v14, v14, v15, v19
	v_div_fixup_f32 v68, v14, v3, 1.0
	v_mov_b32_e32 v14, v65
	v_mov_b32_e32 v15, v29
	v_mov_b32_e32 v26, v67
	v_pk_mul_f32 v[14:15], v[14:15], v[68:69] op_sel_hi:[1,0]
	v_pk_mul_f32 v[26:27], v[26:27], v[68:69] op_sel_hi:[1,0]
	v_cndmask_b32_e64 v3, 0, 1, s[30:31]
	s_waitcnt vmcnt(0)
;     ...
;             const float rstd = 1.f / sqrtf(wave_sum(s2) * (1.f / D) + LN_EPS);
; #pragma unroll
;             for (int j = 0; j < 8; ++j) { const f32x4 gg = ((const f32x4*)g)[F.lane + 64 * j], bb = ((const f32x4*)b)[F.lane + 64 * j]; v[j] = v[j] * rstd * gg + bb; if (WX || m >= ML) ((f32x4*)xr)[F.lane + 64 * j] = v[j]; }
;             if (!WX && m < ML && F.lane == 0) *(v2f*)(WSP(float, WS_STATS) + 2 * m) = (v2f){mean, rstd};
	v_pk_fma_f32 v[34:35], v[34:35], v[26:27], v[72:73]
	v_cmp_ne_u32_e64 s[4:5], 1, v3
	s_andn2_b64 vcc, exec, s[30:31]
	v_pk_fma_f32 v[32:33], v[32:33], v[14:15], v[70:71]
	s_cbranch_vccnz .LBB0_81
	global_store_dwordx4 v[56:57], v[32:35], off
.LBB0_81:
	s_nop 0
	s_nop 0
	v_mov_b32_e32 v65, v28
	v_mov_b32_e32 v69, v68
	v_mov_b32_e32 v14, v68
	v_mov_b32_e32 v15, v68
	v_mov_b32_e32 v67, v30
	v_pk_mul_f32 v[26:27], v[66:67], v[14:15]
	v_pk_mul_f32 v[30:31], v[64:65], v[68:69]
	s_and_b64 vcc, exec, s[4:5]
	s_nop 0
	v_pk_fma_f32 v[28:29], v[26:27], v[162:163], v[166:167]
	v_pk_fma_f32 v[26:27], v[30:31], v[160:161], v[164:165]
	s_cbranch_vccnz .LBB0_83
	global_store_dwordx4 v[56:57], v[26:29], off offset:1024
.LBB0_83:
	s_nop 0
	s_nop 0
	v_mov_b32_e32 v30, v24
	v_mov_b32_e32 v31, v36
	v_mov_b32_e32 v24, v37
	v_pk_mul_f32 v[14:15], v[24:25], v[14:15]
	v_pk_mul_f32 v[24:25], v[30:31], v[68:69]
	s_and_b64 vcc, exec, s[4:5]
	s_nop 0
	v_pk_fma_f32 v[38:39], v[14:15], v[170:171], v[174:175]
	v_pk_fma_f32 v[36:37], v[24:25], v[168:169], v[172:173]
	s_cbranch_vccnz .LBB0_85
	global_store_dwordx4 v[56:57], v[36:39], off offset:2048
.LBB0_85:
	s_nop 0
	s_nop 0
	v_mov_b32_e32 v14, v68
	v_mov_b32_e32 v15, v68
	v_pk_mul_f32 v[20:21], v[20:21], v[68:69]
	v_pk_mul_f32 v[22:23], v[22:23], v[14:15]
	s_and_b64 vcc, exec, s[4:5]
	s_nop 0
	v_pk_fma_f32 v[24:25], v[22:23], v[178:179], v[182:183]
	v_pk_fma_f32 v[22:23], v[20:21], v[176:177], v[180:181]
	s_cbranch_vccnz .LBB0_87
	global_store_dwordx4 v[56:57], v[22:25], off offset:3072
.LBB0_87:
	s_nop 0
	s_nop 0
	v_mov_b32_e32 v17, v60
	v_mov_b32_e32 v19, v62
	v_pk_mul_f32 v[14:15], v[18:19], v[14:15]
	v_pk_mul_f32 v[18:19], v[16:17], v[68:69]
	s_and_b64 vcc, exec, s[4:5]
	s_nop 0
	v_pk_fma_f32 v[16:17], v[14:15], v[186:187], v[190:191]
	v_pk_fma_f32 v[14:15], v[18:19], v[184:185], v[188:189]
	s_cbranch_vccnz .LBB0_89
	s_mov_b64 s[30:31], 0x1000
	v_lshl_add_u64 v[18:19], v[56:57], 0, s[30:31]
	global_store_dwordx4 v[18:19], v[14:17], off
.LBB0_89:
	s_nop 0
	s_nop 0
	s_nop 0
	v_mov_b32_e32 v64, v12
	v_mov_b32_e32 v65, v58
	v_mov_b32_e32 v30, v68
	v_mov_b32_e32 v31, v68
	v_mov_b32_e32 v12, v59
	v_pk_mul_f32 v[12:13], v[12:13], v[30:31]
	v_pk_mul_f32 v[58:59], v[64:65], v[68:69]
	s_and_b64 vcc, exec, s[4:5]
	s_nop 0
	v_pk_fma_f32 v[20:21], v[12:13], v[198:199], v[202:203]
	v_pk_fma_f32 v[18:19], v[58:59], v[196:197], v[200:201]
	s_cbranch_vccnz .LBB0_91
	s_mov_b64 s[30:31], 0x1400
	v_lshl_add_u64 v[12:13], v[56:57], 0, s[30:31]
	global_store_dwordx4 v[12:13], v[18:21], off
.LBB0_91:
	s_nop 0
	s_nop 0
	v_pk_mul_f32 v[10:11], v[10:11], v[30:31]
	v_pk_mul_f32 v[8:9], v[8:9], v[68:69]
	s_and_b64 vcc, exec, s[4:5]
	s_nop 0
	v_pk_fma_f32 v[10:11], v[10:11], v[206:207], v[210:211]
	v_pk_fma_f32 v[8:9], v[8:9], v[204:205], v[208:209]
	s_cbranch_vccnz .LBB0_93
	s_mov_b64 s[30:31], 0x1800
	v_lshl_add_u64 v[12:13], v[56:57], 0, s[30:31]
	global_store_dwordx4 v[12:13], v[8:11], off
.LBB0_93:
	s_nop 0
	s_nop 0
	v_mov_b32_e32 v12, v68
	v_mov_b32_e32 v13, v68
	v_pk_mul_f32 v[4:5], v[4:5], v[68:69]
	v_pk_mul_f32 v[6:7], v[6:7], v[12:13]
	s_and_b64 vcc, exec, s[4:5]
	s_nop 0
	v_pk_fma_f32 v[6:7], v[6:7], v[214:215], v[218:219]
	v_pk_fma_f32 v[4:5], v[4:5], v[212:213], v[216:217]
	s_cbranch_vccnz .LBB0_95
	s_mov_b64 s[4:5], 0x1c00
	v_lshl_add_u64 v[12:13], v[56:57], 0, s[4:5]
	global_store_dwordx4 v[12:13], v[4:7], off

;     ...
;         if (MODH) {
;             float s = 0.f;
; #pragma unroll
;             for (int j = 0; j < 8; ++j) s += (v[j].x + v[j].y) + (v[j].z + v[j].w);
;             const float mean = wave_sum(s) * (1.f / D); float s2 = 0.f;
; #pragma unroll
;             for (int j = 0; j < 8; ++j) { v[j] = v[j] - mean; s2 += (v[j].x * v[j].x + v[j].y * v[j].y) + (v[j].z * v[j].z + v[j].w * v[j].w); }
;             const float rstd = 1.f / sqrtf(wave_sum(s2) * (1.f / D) + LN_EPS);
.LBB0_1155:
	s_or_b64 exec, exec, s[4:5]
	v_mov_b32_e32 v4, v32
	v_mov_b32_e32 v5, v26
	v_mov_b32_e32 v18, v33
	v_mov_b32_e32 v19, v27
	v_pk_add_f32 v[4:5], v[4:5], v[18:19]
	v_mov_b32_e32 v18, v34
	v_mov_b32_e32 v19, v28
	v_mov_b32_e32 v24, v35
	v_mov_b32_e32 v25, v29
	v_pk_add_f32 v[18:19], v[18:19], v[24:25]
	v_mov_b32_e32 v24, v36
	v_pk_add_f32 v[4:5], v[4:5], v[18:19]
	v_mov_b32_e32 v18, v37
	v_mov_b32_e32 v19, v38
	v_mov_b32_e32 v25, v39
	v_pk_add_f32 v[18:19], v[18:19], v[24:25]
	v_add_f32_e32 v3, 0, v4
	v_pk_add_f32 v[18:19], v[18:19], v[18:19] op_sel:[0,1] op_sel_hi:[1,0]
	v_add_f32_e32 v4, v3, v5
	v_add_f32_e32 v24, v20, v21
	v_add_f32_e32 v30, v22, v23
	v_mov_b32_e32 v5, v14
	v_mov_b32_e32 v19, v15
	v_mov_b32_e32 v25, v16
	v_mov_b32_e32 v31, v17
	v_pk_add_f32 v[4:5], v[4:5], v[18:19]
	v_pk_add_f32 v[18:19], v[24:25], v[30:31]
	v_mov_b32_e32 v24, v40
	v_pk_add_f32 v[4:5], v[4:5], v[18:19]
	v_mov_b32_e32 v18, v41
	v_mov_b32_e32 v19, v42
	v_mov_b32_e32 v25, v43
	v_pk_add_f32 v[18:19], v[18:19], v[24:25]
	v_pk_add_f32 v[4:5], v[4:5], v[4:5] op_sel:[0,1] op_sel_hi:[1,0]
	v_pk_add_f32 v[18:19], v[18:19], v[18:19] op_sel:[0,1] op_sel_hi:[1,0]
	v_add_f32_e32 v24, v6, v7
	v_add_f32_e32 v30, v8, v9
	v_mov_b32_e32 v5, v10
	v_mov_b32_e32 v19, v11
	v_mov_b32_e32 v25, v12
	v_mov_b32_e32 v31, v13
	v_pk_add_f32 v[4:5], v[4:5], v[18:19]
	v_pk_add_f32 v[18:19], v[24:25], v[30:31]
	s_nop 0
	v_pk_add_f32 v[4:5], v[4:5], v[18:19]
	s_nop 0
	v_add_f32_e32 v3, v4, v5
	v_mov_b32_e32 v4, v2
	s_nop 0
	v_add_f32_dpp v3, v3, v3 quad_perm:[1,0,3,2] row_mask:0xf bank_mask:0xf bound_ctrl:1
	s_nop 1
	v_add_f32_dpp v3, v3, v3 quad_perm:[2,3,0,1] row_mask:0xf bank_mask:0xf bound_ctrl:1
	s_nop 1
	v_add_f32_dpp v3, v3, v3 row_half_mirror row_mask:0xf bank_mask:0xf bound_ctrl:1
	s_nop 1
	v_add_f32_dpp v3, v3, v3 row_mirror row_mask:0xf bank_mask:0xf bound_ctrl:1
	s_nop 1
	v_mov_b32_dpp v4, v3 row_bcast:15 row_mask:0xa bank_mask:0xf
	v_add_f32_e32 v3, v3, v4
	v_mov_b32_e32 v4, v2
	s_nop 1
	v_mov_b32_dpp v4, v3 row_bcast:31 row_mask:0xc bank_mask:0xf
	v_add_f32_e32 v3, v3, v4
	s_nop 0
	v_readlane_b32 s4, v3, 63
	s_nop 1
	v_fmac_f32_e32 v35, s4, v224
	v_fmac_f32_e32 v33, s4, v224
	v_fma_f32 v34, s4, v224, v34
	v_fma_f32 v32, s4, v224, v32
	v_mul_f32_e32 v3, v33, v33
	v_mul_f32_e32 v4, v35, v35
	v_fmac_f32_e32 v3, v32, v32
	v_fmac_f32_e32 v4, v34, v34
	v_fmac_f32_e32 v29, s4, v224
	v_fmac_f32_e32 v27, s4, v224
	v_add_f32_e32 v3, v3, v4
	v_fma_f32 v28, s4, v224, v28
	v_fma_f32 v26, s4, v224, v26
	v_mul_f32_e32 v4, v27, v27
	v_mul_f32_e32 v5, v29, v29
	v_fmac_f32_e32 v4, v26, v26
	v_fmac_f32_e32 v5, v28, v28
	v_add_f32_e32 v4, v4, v5
	v_fmac_f32_e32 v39, s4, v224
	v_fmac_f32_e32 v37, s4, v224
	v_add_f32_e32 v3, v3, v4
	v_fma_f32 v38, s4, v224, v38
	v_fma_f32 v36, s4, v224, v36
	v_mul_f32_e32 v4, v37, v37
	v_mul_f32_e32 v5, v39, v39
	v_fmac_f32_e32 v4, v36, v36
	v_fmac_f32_e32 v5, v38, v38
	v_add_f32_e32 v4, v4, v5
	v_fmac_f32_e32 v23, s4, v224
	v_fmac_f32_e32 v21, s4, v224
	v_add_f32_e32 v3, v4, v3
	v_fma_f32 v22, s4, v224, v22
	v_fma_f32 v20, s4, v224, v20
	v_mul_f32_e32 v4, v21, v21
	v_mul_f32_e32 v5, v23, v23
	v_fmac_f32_e32 v4, v20, v20
	v_fmac_f32_e32 v5, v22, v22
	v_add_f32_e32 v4, v4, v5
	v_fmac_f32_e32 v17, s4, v224
	v_fmac_f32_e32 v15, s4, v224
	v_add_f32_e32 v3, v4, v3
	v_fma_f32 v16, s4, v224, v16
	v_fma_f32 v14, s4, v224, v14
	v_mul_f32_e32 v4, v15, v15
	v_mul_f32_e32 v5, v17, v17
	v_fmac_f32_e32 v4, v14, v14
	v_fmac_f32_e32 v5, v16, v16
	v_add_f32_e32 v4, v4, v5
	v_fmac_f32_e32 v43, s4, v224
	v_fmac_f32_e32 v41, s4, v224
	v_add_f32_e32 v3, v4, v3
	v_fma_f32 v42, s4, v224, v42
	v_fma_f32 v40, s4, v224, v40
	v_mul_f32_e32 v4, v41, v41
	v_mul_f32_e32 v5, v43, v43
	v_fmac_f32_e32 v4, v40, v40
	v_fmac_f32_e32 v5, v42, v42
	v_add_f32_e32 v4, v4, v5
	v_fmac_f32_e32 v9, s4, v224
	v_fmac_f32_e32 v7, s4, v224
	v_add_f32_e32 v3, v4, v3
	v_fma_f32 v8, s4, v224, v8
	v_fma_f32 v6, s4, v224, v6
	v_mul_f32_e32 v4, v7, v7
	v_mul_f32_e32 v5, v9, v9
	v_fmac_f32_e32 v4, v6, v6
	v_fmac_f32_e32 v5, v8, v8
	v_add_f32_e32 v4, v4, v5
	v_fmac_f32_e32 v13, s4, v224
	v_fmac_f32_e32 v11, s4, v224
	v_add_f32_e32 v3, v4, v3
	v_fma_f32 v12, s4, v224, v12
	v_fma_f32 v10, s4, v224, v10
	v_mul_f32_e32 v4, v11, v11
	v_mul_f32_e32 v5, v13, v13
	v_fmac_f32_e32 v4, v10, v10
	v_fmac_f32_e32 v5, v12, v12
	v_add_f32_e32 v4, v4, v5
	v_add_f32_e32 v3, v4, v3
	v_mov_b32_e32 v4, v2
	s_nop 0
	v_add_f32_dpp v3, v3, v3 quad_perm:[1,0,3,2] row_mask:0xf bank_mask:0xf bound_ctrl:1
	s_nop 1
	v_add_f32_dpp v3, v3, v3 quad_perm:[2,3,0,1] row_mask:0xf bank_mask:0xf bound_ctrl:1
	s_nop 1
	v_add_f32_dpp v3, v3, v3 row_half_mirror row_mask:0xf bank_mask:0xf bound_ctrl:1
	s_nop 1
	v_add_f32_dpp v3, v3, v3 row_mirror row_mask:0xf bank_mask:0xf bound_ctrl:1
	s_nop 1
	v_mov_b32_dpp v4, v3 row_bcast:15 row_mask:0xa bank_mask:0xf
	v_add_f32_e32 v3, v3, v4
	v_mov_b32_e32 v4, v2
	s_nop 1
	v_mov_b32_dpp v4, v3 row_bcast:31 row_mask:0xc bank_mask:0xf
	v_add_f32_e32 v3, v3, v4
	s_nop 0
	v_readlane_b32 s4, v3, 63
	s_nop 1
	v_fma_f32 v3, s4, v226, v225
	v_cmp_gt_f32_e32 vcc, s64, v3
	v_mul_f32_e32 v4, 0x4f800000, v3
	s_nop 0
	v_cndmask_b32_e32 v3, v3, v4, vcc
	v_sqrt_f32_e32 v4, v3
	s_nop 0
	v_add_u32_e32 v5, -1, v4
	v_fma_f32 v18, -v5, v4, v3
	v_cmp_ge_f32_e64 s[4:5], 0, v18
	v_add_u32_e32 v18, 1, v4
	s_nop 0
	v_cndmask_b32_e64 v5, v4, v5, s[4:5]
	v_fma_f32 v4, -v18, v4, v3
	v_cmp_lt_f32_e64 s[4:5], 0, v4
	s_nop 1
	v_cndmask_b32_e64 v4, v5, v18, s[4:5]
	v_mul_f32_e32 v5, 0x37800000, v4
	v_cndmask_b32_e32 v4, v4, v5, vcc
	v_cmp_class_f32_e32 vcc, v3, v227
	s_nop 1
	v_cndmask_b32_e32 v3, v4, v3, vcc
	v_div_scale_f32 v4, s[4:5], v3, v3, 1.0
; __device__ __forceinline__ unsigned pk2(float lo, float hi) { const f32x2 v = {lo, hi}; return __builtin_bit_cast(unsigned, __builtin_convertvector(v, bf2n_t_)); }
;     ...
;             const float rstd = 1.f / sqrtf(wave_sum(s2) * (1.f / D) + LN_EPS);
;             const int bsel = m < ML ? (m >> 11) : 8;
;             const f32x4* shp = (const f32x4*)(mods_l + (size_t)bsel * 18432 + kshift * 2048);
;             const f32x4* scp = (const f32x4*)(mods_l + (size_t)bsel * 18432 + kscale * 2048);
;             v2u* hp = (v2u*)(HB + (size_t)m * D);
; #pragma unroll
;             for (int j = 0; j < 8; ++j) { const f32x4 sh = shp[F.lane + 64 * j], scl = scp[F.lane + 64 * j]; const f32x4 o = v[j] * rstd * (scl + 1.0f) + sh;
;                 v2u w; w.x = pk2(o.x, o.y); w.y = pk2(o.z, o.w); hp[F.lane + 64 * j] = w; }
	v_rcp_f32_e32 v5, v4
	s_min_i32 s4, s24, 0x4000
	s_ashr_i32 s4, s4, 11
	s_mul_hi_i32 s5, s4, 0x12000
	v_fma_f32 v18, -v4, v5, 1.0
	v_fmac_f32_e32 v5, v18, v5
	v_div_scale_f32 v18, vcc, 1.0, v3, 1.0
	s_mul_i32 s4, s4, 0x12000
	v_mul_f32_e32 v19, v18, v5
	s_add_u32 s4, s16, s4
	v_fma_f32 v24, -v4, v19, v18
	s_addc_u32 s5, s17, s5
	v_fmac_f32_e32 v19, v24, v5
	v_lshl_add_u64 v[24:25], v[0:1], 4, s[4:5]
	s_mov_b64 s[4:5], 0xc000
	v_fma_f32 v4, -v4, v19, v18
	v_lshl_add_u64 v[30:31], v[24:25], 0, s[4:5]
	s_mov_b32 s4, 0xd000
	v_div_fmas_f32 v4, v4, v5, v19
	v_add_co_u32_e32 v18, vcc, s4, v24
	s_mov_b64 s[4:5], 0xe000
	s_nop 0
	v_addc_co_u32_e32 v19, vcc, 0, v25, vcc
	v_lshl_add_u64 v[86:87], v[24:25], 0, s[4:5]
	s_mov_b32 s4, 0xf000
	v_add_co_u32_e32 v24, vcc, s4, v24
	global_load_dwordx4 v[44:47], v[18:19], off offset:-4096
	s_nop 0
	v_addc_co_u32_e32 v25, vcc, 0, v25, vcc
	global_load_dwordx4 v[48:51], v[24:25], off offset:-4096
	global_load_dwordx4 v[104:107], v[30:31], off offset:1024
	global_load_dwordx4 v[108:111], v[86:87], off offset:1024
	global_load_dwordx4 v[112:115], v[30:31], off offset:2048
	global_load_dwordx4 v[116:119], v[86:87], off offset:2048
	global_load_dwordx4 v[120:123], v[30:31], off offset:3072
	global_load_dwordx4 v[124:127], v[86:87], off offset:3072
	global_load_dwordx4 v[128:131], v[18:19], off
	global_load_dwordx4 v[132:135], v[24:25], off
	global_load_dwordx4 v[136:139], v[18:19], off offset:1024
	global_load_dwordx4 v[140:143], v[24:25], off offset:1024
	global_load_dwordx4 v[144:147], v[18:19], off offset:2048
	global_load_dwordx4 v[148:151], v[24:25], off offset:2048
	global_load_dwordx4 v[152:155], v[18:19], off offset:3072
	global_load_dwordx4 v[156:159], v[24:25], off offset:3072
	v_div_fixup_f32 v4, v4, v3, 1.0
	v_pk_mul_f32 v[32:33], v[32:33], v[4:5] op_sel_hi:[1,0]
	v_pk_mul_f32 v[34:35], v[34:35], v[4:5] op_sel_hi:[1,0]
	v_pk_mul_f32 v[26:27], v[26:27], v[4:5] op_sel_hi:[1,0]
	v_pk_mul_f32 v[28:29], v[28:29], v[4:5] op_sel_hi:[1,0]
	v_pk_mul_f32 v[36:37], v[36:37], v[4:5] op_sel_hi:[1,0]
	v_pk_mul_f32 v[38:39], v[38:39], v[4:5] op_sel_hi:[1,0]
	v_pk_mul_f32 v[20:21], v[20:21], v[4:5] op_sel_hi:[1,0]
	v_pk_mul_f32 v[22:23], v[22:23], v[4:5] op_sel_hi:[1,0]
	v_pk_mul_f32 v[14:15], v[14:15], v[4:5] op_sel_hi:[1,0]
	v_pk_mul_f32 v[16:17], v[16:17], v[4:5] op_sel_hi:[1,0]
	v_pk_mul_f32 v[6:7], v[6:7], v[4:5] op_sel_hi:[1,0]
	v_pk_mul_f32 v[8:9], v[8:9], v[4:5] op_sel_hi:[1,0]
	v_pk_mul_f32 v[10:11], v[10:11], v[4:5] op_sel_hi:[1,0]
	s_add_u32 s24, s24, s0
	s_addc_u32 s25, s25, s1
	s_add_i32 s20, s20, s37
	s_cmp_lt_i32 s24, s31
	s_waitcnt vmcnt(14)
	v_pk_add_f32 v[50:51], v[50:51], 1.0 op_sel_hi:[1,0]
	v_pk_add_f32 v[48:49], v[48:49], 1.0 op_sel_hi:[1,0]
	v_pk_fma_f32 v[34:35], v[50:51], v[34:35], v[46:47]
	v_pk_fma_f32 v[32:33], v[48:49], v[32:33], v[44:45]
	s_nop 0
	v_cvt_pk_bf16_f32 v32, v32, v33
	v_cvt_pk_bf16_f32 v33, v34, v35
	global_store_dwordx2 v[84:85], v[32:33], off
	s_nop 0
	s_nop 0
	s_nop 0
	s_waitcnt vmcnt(13)
	v_pk_add_f32 v[46:47], v[110:111], 1.0 op_sel_hi:[1,0]
	v_pk_add_f32 v[44:45], v[108:109], 1.0 op_sel_hi:[1,0]
	v_pk_fma_f32 v[28:29], v[46:47], v[28:29], v[106:107]
	v_pk_fma_f32 v[26:27], v[44:45], v[26:27], v[104:105]
	s_nop 0
	v_cvt_pk_bf16_f32 v26, v26, v27
	v_cvt_pk_bf16_f32 v27, v28, v29
	global_store_dwordx2 v[84:85], v[26:27], off offset:512
	s_nop 0
	s_nop 0
	s_nop 0
	s_waitcnt vmcnt(12)
	v_pk_add_f32 v[34:35], v[118:119], 1.0 op_sel_hi:[1,0]
	v_pk_add_f32 v[32:33], v[116:117], 1.0 op_sel_hi:[1,0]
	v_pk_fma_f32 v[28:29], v[38:39], v[34:35], v[114:115]
	v_pk_fma_f32 v[26:27], v[36:37], v[32:33], v[112:113]
	s_nop 0
	v_cvt_pk_bf16_f32 v26, v26, v27
	v_cvt_pk_bf16_f32 v27, v28, v29
	global_store_dwordx2 v[84:85], v[26:27], off offset:1024
	s_nop 0
	s_nop 0
	s_nop 0
	s_waitcnt vmcnt(11)
	v_pk_add_f32 v[32:33], v[126:127], 1.0 op_sel_hi:[1,0]
	v_pk_add_f32 v[30:31], v[124:125], 1.0 op_sel_hi:[1,0]
	v_pk_fma_f32 v[22:23], v[22:23], v[32:33], v[122:123]
	v_pk_fma_f32 v[20:21], v[20:21], v[30:31], v[120:121]
	s_nop 0
	v_cvt_pk_bf16_f32 v20, v20, v21
	v_cvt_pk_bf16_f32 v21, v22, v23
	global_store_dwordx2 v[84:85], v[20:21], off offset:1536
	s_nop 0
	s_nop 0
	s_nop 0
	s_waitcnt vmcnt(10)
	v_pk_add_f32 v[28:29], v[134:135], 1.0 op_sel_hi:[1,0]
	v_pk_add_f32 v[26:27], v[132:133], 1.0 op_sel_hi:[1,0]
	v_pk_fma_f32 v[16:17], v[16:17], v[28:29], v[130:131]
	v_pk_fma_f32 v[14:15], v[14:15], v[26:27], v[128:129]
	v_pk_mul_f32 v[26:27], v[40:41], v[4:5] op_sel_hi:[1,0]
	v_cvt_pk_bf16_f32 v14, v14, v15
	v_cvt_pk_bf16_f32 v15, v16, v17
	global_store_dwordx2 v[84:85], v[14:15], off offset:2048
	s_nop 0
	s_nop 0
	s_nop 0
	v_pk_mul_f32 v[28:29], v[42:43], v[4:5] op_sel_hi:[1,0]
	v_pk_mul_f32 v[4:5], v[12:13], v[4:5] op_sel_hi:[1,0]
	s_waitcnt vmcnt(9)
	v_pk_add_f32 v[22:23], v[142:143], 1.0 op_sel_hi:[1,0]
	v_pk_add_f32 v[20:21], v[140:141], 1.0 op_sel_hi:[1,0]
	v_pk_fma_f32 v[16:17], v[28:29], v[22:23], v[138:139]
	v_pk_fma_f32 v[14:15], v[26:27], v[20:21], v[136:137]
	s_nop 0
	v_cvt_pk_bf16_f32 v14, v14, v15
	v_cvt_pk_bf16_f32 v15, v16, v17
	global_store_dwordx2 v[84:85], v[14:15], off offset:2560
	s_nop 0
	s_nop 0
	s_nop 0
	s_waitcnt vmcnt(8)
	v_pk_add_f32 v[22:23], v[150:151], 1.0 op_sel_hi:[1,0]
	v_pk_add_f32 v[20:21], v[148:149], 1.0 op_sel_hi:[1,0]
	v_pk_fma_f32 v[8:9], v[8:9], v[22:23], v[146:147]
	v_pk_fma_f32 v[6:7], v[6:7], v[20:21], v[144:145]
	s_nop 0
	v_cvt_pk_bf16_f32 v6, v6, v7
	v_cvt_pk_bf16_f32 v7, v8, v9
	global_store_dwordx2 v[84:85], v[6:7], off offset:3072
	s_nop 0
	s_nop 0
	s_nop 0
	s_waitcnt vmcnt(7)
	v_pk_add_f32 v[12:13], v[158:159], 1.0 op_sel_hi:[1,0]
	v_pk_add_f32 v[14:15], v[156:157], 1.0 op_sel_hi:[1,0]
	v_pk_fma_f32 v[4:5], v[4:5], v[12:13], v[154:155]
	v_pk_fma_f32 v[6:7], v[10:11], v[14:15], v[152:153]
	s_nop 0
	v_cvt_pk_bf16_f32 v6, v6, v7
	v_cvt_pk_bf16_f32 v7, v4, v5
	global_store_dwordx2 v[84:85], v[6:7], off offset:3584
	v_lshl_add_u64 v[84:85], v[84:85], 0, s[22:23]
	s_cbranch_scc0 .LBB0_1177
; __device__ __forceinline__ float* xrow(const Frame& F, int m) { return m < ML ? (float*)(F.out + (size_t)m * D) : WSP(float, WS_XC) + (size_t)(m - ML) * D; }
;     ...
;     for (int m = gw; m < nrows; m += NGW) {
;         float* xr = xrow(F, m);
;         const float* xs = (m < ML) ? (src_l ? src_l + (size_t)m * D : xr) : (src_c ? src_c + (size_t)(m - ML) * D : xr);
;         f32x4 v[8];
; #pragma unroll
;         for (int j = 0; j < 8; ++j) v[j] = ((const f32x4*)xs)[F.lane + 64 * j];
;         if (POST && part != nullptr && m >= ML) {
;             const v2u* pp = (const v2u*)(part + (size_t)(m - ML) * D);
; #pragma unroll
;             for (int j = 0; j < 8; ++j) { const int o = F.lane + 64 * j; const v2u p0 = pp[o], p1 = pp[o + (size_t)MC * D / 4], p2 = pp[o + 2 * ((size_t)MC * D / 4)], p3 = pp[o + 3 * ((size_t)MC * D / 4)];
;                 const f32x4 ps = ((f32x4){bflo(p0.x), bfhi(p0.x), bflo(p0.y), bfhi(p0.y)} + (f32x4){bflo(p1.x), bfhi(p1.x), bflo(p1.y), bfhi(p1.y)}) + ((f32x4){bflo(p2.x), bfhi(p2.x), bflo(p2.y), bfhi(p2.y)} + (f32x4){bflo(p3.x), bfhi(p3.x), bflo(p3.y), bfhi(p3.y)});
;                 v[j] = v[j] * ALPHA + ((const f32x4*)pmod)[o] * pcoef * ps; }
.LBB0_1156:
	s_add_i32 s66, s24, 0xffffc000
	s_cmpk_lt_i32 s24, 0x4000
	s_cselect_b64 s[26:27], -1, 0
	s_and_b64 s[4:5], s[26:27], exec
	s_cselect_b32 s5, s25, 0
	s_cselect_b32 s4, s24, s66
	s_cselect_b32 s11, s15, s34
	s_cselect_b32 s21, s14, s33
	s_lshl_b64 s[4:5], s[4:5], 13
	s_add_u32 s4, s21, s4
	s_addc_u32 s5, s11, s5
	v_lshl_add_u64 v[44:45], v[0:1], 4, s[4:5]
	v_add_co_u32_e32 v4, vcc, 0x1000, v44
	global_load_dwordx4 v[28:31], v[44:45], off
	global_load_dwordx4 v[32:35], v[44:45], off offset:1024
	global_load_dwordx4 v[24:27], v[44:45], off offset:2048
	global_load_dwordx4 v[20:23], v[44:45], off offset:3072
	v_addc_co_u32_e32 v5, vcc, 0, v45, vcc
	global_load_dwordx4 v[16:19], v[4:5], off
	global_load_dwordx4 v[12:15], v[4:5], off offset:1024
	global_load_dwordx4 v[8:11], v[4:5], off offset:2048
	s_nop 0
	global_load_dwordx4 v[4:7], v[4:5], off offset:3072
	s_cmpk_gt_i32 s24, 0x3fff
	s_cselect_b64 s[28:29], -1, 0
	s_and_b64 s[4:5], s[18:19], s[28:29]
	s_andn2_b64 vcc, exec, s[4:5]
	s_cbranch_vccnz .LBB0_1158
	s_lshl_b64 s[4:5], s[66:67], 12
	v_lshl_add_u64 v[48:49], v[82:83], 0, s[4:5]
	v_add_co_u32_e32 v46, vcc, 0x800000, v48
	global_load_dwordx2 v[36:37], v[48:49], off
	s_nop 0
	v_addc_co_u32_e32 v47, vcc, 0, v49, vcc
	v_add_co_u32_e32 v42, vcc, 0x1000000, v48
	global_load_dwordx2 v[38:39], v[46:47], off
	s_nop 0
	v_addc_co_u32_e32 v43, vcc, 0, v49, vcc
	v_add_co_u32_e32 v40, vcc, 0x1800000, v48
	global_load_dwordx2 v[50:51], v[42:43], off
	s_nop 0
	v_addc_co_u32_e32 v41, vcc, 0, v49, vcc
	global_load_dwordx2 v[86:87], v[40:41], off
	global_load_dwordx4 v[104:107], v[72:73], off
	global_load_dwordx2 v[136:137], v[48:49], off offset:512
	global_load_dwordx2 v[138:139], v[46:47], off offset:512
	global_load_dwordx2 v[140:141], v[42:43], off offset:512
	global_load_dwordx2 v[142:143], v[40:41], off offset:512
	global_load_dwordx4 v[108:111], v[72:73], off offset:1024
	global_load_dwordx2 v[144:145], v[48:49], off offset:1024
	global_load_dwordx2 v[146:147], v[46:47], off offset:1024
	global_load_dwordx2 v[148:149], v[42:43], off offset:1024
	global_load_dwordx2 v[150:151], v[40:41], off offset:1024
	global_load_dwordx4 v[112:115], v[72:73], off offset:2048
	global_load_dwordx2 v[152:153], v[48:49], off offset:1536
	global_load_dwordx2 v[154:155], v[46:47], off offset:1536
	global_load_dwordx2 v[156:157], v[42:43], off offset:1536
	global_load_dwordx2 v[158:159], v[40:41], off offset:1536
	global_load_dwordx4 v[116:119], v[72:73], off offset:3072
	global_load_dwordx2 v[160:161], v[48:49], off offset:2048
	global_load_dwordx2 v[162:163], v[46:47], off offset:2048
	global_load_dwordx2 v[164:165], v[42:43], off offset:2048
	global_load_dwordx2 v[166:167], v[40:41], off offset:2048
	global_load_dwordx4 v[120:123], v[74:75], off
	global_load_dwordx2 v[168:169], v[48:49], off offset:2560
	global_load_dwordx2 v[170:171], v[46:47], off offset:2560
	global_load_dwordx2 v[172:173], v[42:43], off offset:2560
	global_load_dwordx2 v[174:175], v[40:41], off offset:2560
	global_load_dwordx4 v[124:127], v[76:77], off
	global_load_dwordx2 v[176:177], v[48:49], off offset:3072
	global_load_dwordx2 v[178:179], v[46:47], off offset:3072
	global_load_dwordx2 v[180:181], v[42:43], off offset:3072
	global_load_dwordx2 v[182:183], v[40:41], off offset:3072
	global_load_dwordx4 v[128:131], v[78:79], off
	global_load_dwordx2 v[184:185], v[48:49], off offset:3584
	global_load_dwordx2 v[186:187], v[46:47], off offset:3584
	global_load_dwordx2 v[188:189], v[42:43], off offset:3584
	global_load_dwordx2 v[190:191], v[40:41], off offset:3584
	global_load_dwordx4 v[132:135], v[80:81], off
	s_waitcnt vmcnt(36)
	v_lshlrev_b32_e32 v88, 16, v36
	v_and_b32_e32 v89, 0xffff0000, v36
	v_lshlrev_b32_e32 v36, 16, v37
	v_and_b32_e32 v37, 0xffff0000, v37
	v_lshlrev_b32_e32 v90, 16, v38
	v_and_b32_e32 v91, 0xffff0000, v38
	v_lshlrev_b32_e32 v38, 16, v39
	v_and_b32_e32 v39, 0xffff0000, v39
	v_pk_add_f32 v[88:89], v[88:89], v[90:91]
	v_pk_add_f32 v[36:37], v[36:37], v[38:39]
	v_lshlrev_b32_e32 v38, 16, v50
	v_and_b32_e32 v39, 0xffff0000, v50
	v_lshlrev_b32_e32 v50, 16, v51
	v_and_b32_e32 v51, 0xffff0000, v51
	v_lshlrev_b32_e32 v90, 16, v86
	v_and_b32_e32 v91, 0xffff0000, v86
	v_lshlrev_b32_e32 v86, 16, v87
	v_and_b32_e32 v87, 0xffff0000, v87
	v_pk_add_f32 v[38:39], v[38:39], v[90:91]
	v_pk_add_f32 v[50:51], v[50:51], v[86:87]
	v_pk_add_f32 v[86:87], v[88:89], v[38:39]
	v_pk_add_f32 v[50:51], v[36:37], v[50:51]
	s_nop 0
	s_waitcnt vmcnt(35)
	v_pk_mul_f32 v[36:37], v[104:105], v[86:87]
	v_pk_mul_f32 v[38:39], v[106:107], v[50:51]
	v_pk_fma_f32 v[28:29], v[28:29], s[38:39], v[36:37] op_sel_hi:[1,0,1]
	v_pk_fma_f32 v[30:31], v[30:31], s[38:39], v[38:39] op_sel_hi:[1,0,1]
	s_nop 0
	s_nop 0
	s_nop 0
	s_nop 0
	s_waitcnt vmcnt(34)
	v_lshlrev_b32_e32 v88, 16, v136
	v_and_b32_e32 v89, 0xffff0000, v136
	v_lshlrev_b32_e32 v36, 16, v137
	v_and_b32_e32 v37, 0xffff0000, v137
	s_waitcnt vmcnt(33)
	v_lshlrev_b32_e32 v90, 16, v138
	v_and_b32_e32 v91, 0xffff0000, v138
	v_lshlrev_b32_e32 v38, 16, v139
	v_and_b32_e32 v39, 0xffff0000, v139
	v_pk_add_f32 v[88:89], v[88:89], v[90:91]
	v_pk_add_f32 v[36:37], v[36:37], v[38:39]
	s_waitcnt vmcnt(32)
	v_lshlrev_b32_e32 v38, 16, v140
	v_and_b32_e32 v39, 0xffff0000, v140
	v_lshlrev_b32_e32 v50, 16, v141
	v_and_b32_e32 v51, 0xffff0000, v141
	s_waitcnt vmcnt(31)
	v_lshlrev_b32_e32 v90, 16, v142
	v_and_b32_e32 v91, 0xffff0000, v142
	v_lshlrev_b32_e32 v86, 16, v143
	v_and_b32_e32 v87, 0xffff0000, v143
	v_pk_add_f32 v[38:39], v[38:39], v[90:91]
	v_pk_add_f32 v[50:51], v[50:51], v[86:87]
	v_pk_add_f32 v[86:87], v[88:89], v[38:39]
	v_pk_add_f32 v[50:51], v[36:37], v[50:51]
	s_nop 0
	s_waitcnt vmcnt(30)
;     ...
;             for (int j = 0; j < 8; ++j) { const int o = F.lane + 64 * j; const v2u p0 = pp[o], p1 = pp[o + (size_t)MC * D / 4], p2 = pp[o + 2 * ((size_t)MC * D / 4)], p3 = pp[o + 3 * ((size_t)MC * D / 4)];
;                 const f32x4 ps = ((f32x4){bflo(p0.x), bfhi(p0.x), bflo(p0.y), bfhi(p0.y)} + (f32x4){bflo(p1.x), bfhi(p1.x), bflo(p1.y), bfhi(p1.y)}) + ((f32x4){bflo(p2.x), bfhi(p2.x), bflo(p2.y), bfhi(p2.y)} + (f32x4){bflo(p3.x), bfhi(p3.x), bflo(p3.y), bfhi(p3.y)});
;                 v[j] = v[j] * ALPHA + ((const f32x4*)pmod)[o] * pcoef * ps; }
	v_pk_mul_f32 v[86:87], v[108:109], v[86:87]
	v_pk_mul_f32 v[36:37], v[110:111], v[50:51]
	v_pk_fma_f32 v[38:39], v[32:33], s[38:39], v[86:87] op_sel_hi:[1,0,1]
	v_pk_fma_f32 v[36:37], v[34:35], s[38:39], v[36:37] op_sel_hi:[1,0,1]
	s_nop 0
	s_nop 0
	s_nop 0
	s_nop 0
	s_waitcnt vmcnt(29)
	v_lshlrev_b32_e32 v88, 16, v144
	v_and_b32_e32 v89, 0xffff0000, v144
	v_lshlrev_b32_e32 v32, 16, v145
	v_and_b32_e32 v33, 0xffff0000, v145
	s_waitcnt vmcnt(28)
	v_lshlrev_b32_e32 v90, 16, v146
	v_and_b32_e32 v91, 0xffff0000, v146
	v_lshlrev_b32_e32 v34, 16, v147
	v_and_b32_e32 v35, 0xffff0000, v147
	v_pk_add_f32 v[88:89], v[88:89], v[90:91]
	v_pk_add_f32 v[32:33], v[32:33], v[34:35]
	s_waitcnt vmcnt(27)
	v_lshlrev_b32_e32 v34, 16, v148
	v_and_b32_e32 v35, 0xffff0000, v148
	v_lshlrev_b32_e32 v50, 16, v149
	v_and_b32_e32 v51, 0xffff0000, v149
	s_waitcnt vmcnt(26)
	v_lshlrev_b32_e32 v90, 16, v150
	v_and_b32_e32 v91, 0xffff0000, v150
	v_lshlrev_b32_e32 v86, 16, v151
	v_and_b32_e32 v87, 0xffff0000, v151
	v_pk_add_f32 v[34:35], v[34:35], v[90:91]
	v_pk_add_f32 v[50:51], v[50:51], v[86:87]
	v_pk_add_f32 v[86:87], v[88:89], v[34:35]
	v_pk_add_f32 v[50:51], v[32:33], v[50:51]
	s_nop 0
	s_waitcnt vmcnt(25)
	v_pk_mul_f32 v[32:33], v[112:113], v[86:87]
	v_pk_mul_f32 v[34:35], v[114:115], v[50:51]
	v_pk_fma_f32 v[24:25], v[24:25], s[38:39], v[32:33] op_sel_hi:[1,0,1]
	v_pk_fma_f32 v[26:27], v[26:27], s[38:39], v[34:35] op_sel_hi:[1,0,1]
	s_nop 0
	s_nop 0
	s_nop 0
	s_nop 0
	s_waitcnt vmcnt(24)
	v_lshlrev_b32_e32 v88, 16, v152
	v_and_b32_e32 v89, 0xffff0000, v152
	v_lshlrev_b32_e32 v32, 16, v153
	v_and_b32_e32 v33, 0xffff0000, v153
	s_waitcnt vmcnt(23)
	v_lshlrev_b32_e32 v90, 16, v154
	v_and_b32_e32 v91, 0xffff0000, v154
	v_lshlrev_b32_e32 v34, 16, v155
	v_and_b32_e32 v35, 0xffff0000, v155
	v_pk_add_f32 v[88:89], v[88:89], v[90:91]
	v_pk_add_f32 v[32:33], v[32:33], v[34:35]
	s_waitcnt vmcnt(22)
	v_lshlrev_b32_e32 v34, 16, v156
	v_and_b32_e32 v35, 0xffff0000, v156
	v_lshlrev_b32_e32 v50, 16, v157
	v_and_b32_e32 v51, 0xffff0000, v157
	s_waitcnt vmcnt(21)
	v_lshlrev_b32_e32 v90, 16, v158
	v_and_b32_e32 v91, 0xffff0000, v158
	v_lshlrev_b32_e32 v86, 16, v159
	v_and_b32_e32 v87, 0xffff0000, v159
	v_pk_add_f32 v[34:35], v[34:35], v[90:91]
	v_pk_add_f32 v[50:51], v[50:51], v[86:87]
	v_pk_add_f32 v[86:87], v[88:89], v[34:35]
	v_pk_add_f32 v[50:51], v[32:33], v[50:51]
	s_nop 0
	s_waitcnt vmcnt(20)
	v_pk_mul_f32 v[32:33], v[116:117], v[86:87]
	v_pk_mul_f32 v[34:35], v[118:119], v[50:51]
	v_pk_fma_f32 v[20:21], v[20:21], s[38:39], v[32:33] op_sel_hi:[1,0,1]
	v_pk_fma_f32 v[22:23], v[22:23], s[38:39], v[34:35] op_sel_hi:[1,0,1]
	s_nop 0
	s_nop 0
	s_nop 0
	s_nop 0
	s_waitcnt vmcnt(19)
	v_lshlrev_b32_e32 v88, 16, v160
	v_and_b32_e32 v89, 0xffff0000, v160
	v_lshlrev_b32_e32 v32, 16, v161
	v_and_b32_e32 v33, 0xffff0000, v161
	s_waitcnt vmcnt(18)
	v_lshlrev_b32_e32 v90, 16, v162
	v_and_b32_e32 v91, 0xffff0000, v162
	v_lshlrev_b32_e32 v34, 16, v163
	v_and_b32_e32 v35, 0xffff0000, v163
	v_pk_add_f32 v[88:89], v[88:89], v[90:91]
	v_pk_add_f32 v[32:33], v[32:33], v[34:35]
	s_waitcnt vmcnt(17)
	v_lshlrev_b32_e32 v34, 16, v164
	v_and_b32_e32 v35, 0xffff0000, v164
	v_lshlrev_b32_e32 v50, 16, v165
	v_and_b32_e32 v51, 0xffff0000, v165
	s_waitcnt vmcnt(16)
	v_lshlrev_b32_e32 v90, 16, v166
	v_and_b32_e32 v91, 0xffff0000, v166
	v_lshlrev_b32_e32 v86, 16, v167
	v_and_b32_e32 v87, 0xffff0000, v167
	v_pk_add_f32 v[34:35], v[34:35], v[90:91]
	v_pk_add_f32 v[50:51], v[50:51], v[86:87]
	v_pk_add_f32 v[86:87], v[88:89], v[34:35]
	v_pk_add_f32 v[50:51], v[32:33], v[50:51]
	s_nop 0
	s_waitcnt vmcnt(15)
	v_pk_mul_f32 v[32:33], v[120:121], v[86:87]
	v_pk_mul_f32 v[34:35], v[122:123], v[50:51]
	v_pk_fma_f32 v[16:17], v[16:17], s[38:39], v[32:33] op_sel_hi:[1,0,1]
	v_pk_fma_f32 v[18:19], v[18:19], s[38:39], v[34:35] op_sel_hi:[1,0,1]
	s_nop 0
	s_nop 0
	s_nop 0
	s_nop 0
	s_waitcnt vmcnt(14)
;     ...
;             for (int j = 0; j < 8; ++j) { const int o = F.lane + 64 * j; const v2u p0 = pp[o], p1 = pp[o + (size_t)MC * D / 4], p2 = pp[o + 2 * ((size_t)MC * D / 4)], p3 = pp[o + 3 * ((size_t)MC * D / 4)];
;                 const f32x4 ps = ((f32x4){bflo(p0.x), bfhi(p0.x), bflo(p0.y), bfhi(p0.y)} + (f32x4){bflo(p1.x), bfhi(p1.x), bflo(p1.y), bfhi(p1.y)}) + ((f32x4){bflo(p2.x), bfhi(p2.x), bflo(p2.y), bfhi(p2.y)} + (f32x4){bflo(p3.x), bfhi(p3.x), bflo(p3.y), bfhi(p3.y)});
;                 v[j] = v[j] * ALPHA + ((const f32x4*)pmod)[o] * pcoef * ps; }
	v_lshlrev_b32_e32 v88, 16, v168
	v_and_b32_e32 v89, 0xffff0000, v168
	v_lshlrev_b32_e32 v32, 16, v169
	v_and_b32_e32 v33, 0xffff0000, v169
	s_waitcnt vmcnt(13)
	v_lshlrev_b32_e32 v90, 16, v170
	v_and_b32_e32 v91, 0xffff0000, v170
	v_lshlrev_b32_e32 v34, 16, v171
	v_and_b32_e32 v35, 0xffff0000, v171
	v_pk_add_f32 v[88:89], v[88:89], v[90:91]
	v_pk_add_f32 v[32:33], v[32:33], v[34:35]
	s_waitcnt vmcnt(12)
	v_lshlrev_b32_e32 v34, 16, v172
	v_and_b32_e32 v35, 0xffff0000, v172
	v_lshlrev_b32_e32 v50, 16, v173
	v_and_b32_e32 v51, 0xffff0000, v173
	s_waitcnt vmcnt(11)
	v_lshlrev_b32_e32 v90, 16, v174
	v_and_b32_e32 v91, 0xffff0000, v174
	v_lshlrev_b32_e32 v86, 16, v175
	v_and_b32_e32 v87, 0xffff0000, v175
	v_pk_add_f32 v[34:35], v[34:35], v[90:91]
	v_pk_add_f32 v[50:51], v[50:51], v[86:87]
	v_pk_add_f32 v[86:87], v[88:89], v[34:35]
	v_pk_add_f32 v[50:51], v[32:33], v[50:51]
	s_nop 0
	s_waitcnt vmcnt(10)
	v_pk_mul_f32 v[32:33], v[124:125], v[86:87]
	v_pk_mul_f32 v[34:35], v[126:127], v[50:51]
	v_pk_fma_f32 v[12:13], v[12:13], s[38:39], v[32:33] op_sel_hi:[1,0,1]
	v_pk_fma_f32 v[14:15], v[14:15], s[38:39], v[34:35] op_sel_hi:[1,0,1]
	s_nop 0
	s_nop 0
	s_nop 0
	s_nop 0
	s_waitcnt vmcnt(9)
	v_lshlrev_b32_e32 v88, 16, v176
	v_and_b32_e32 v89, 0xffff0000, v176
	v_lshlrev_b32_e32 v32, 16, v177
	v_and_b32_e32 v33, 0xffff0000, v177
	s_waitcnt vmcnt(8)
	v_lshlrev_b32_e32 v90, 16, v178
	v_and_b32_e32 v91, 0xffff0000, v178
	v_lshlrev_b32_e32 v34, 16, v179
	v_and_b32_e32 v35, 0xffff0000, v179
	v_pk_add_f32 v[88:89], v[88:89], v[90:91]
	v_pk_add_f32 v[32:33], v[32:33], v[34:35]
	s_waitcnt vmcnt(7)
	v_lshlrev_b32_e32 v34, 16, v180
	v_and_b32_e32 v35, 0xffff0000, v180
	v_lshlrev_b32_e32 v50, 16, v181
	v_and_b32_e32 v51, 0xffff0000, v181
	s_waitcnt vmcnt(6)
	v_lshlrev_b32_e32 v90, 16, v182
	v_and_b32_e32 v91, 0xffff0000, v182
	v_lshlrev_b32_e32 v86, 16, v183
	v_and_b32_e32 v87, 0xffff0000, v183
	v_pk_add_f32 v[34:35], v[34:35], v[90:91]
	v_pk_add_f32 v[50:51], v[50:51], v[86:87]
	v_pk_add_f32 v[86:87], v[88:89], v[34:35]
	v_pk_add_f32 v[50:51], v[32:33], v[50:51]
	s_nop 0
	s_waitcnt vmcnt(5)
	v_pk_mul_f32 v[32:33], v[128:129], v[86:87]
	v_pk_mul_f32 v[34:35], v[130:131], v[50:51]
	v_pk_fma_f32 v[8:9], v[8:9], s[38:39], v[32:33] op_sel_hi:[1,0,1]
	v_pk_fma_f32 v[10:11], v[10:11], s[38:39], v[34:35] op_sel_hi:[1,0,1]
	s_nop 0
	s_nop 0
	s_nop 0
	s_nop 0
	s_nop 0
	s_nop 0
	v_mov_b32_e32 v87, v30
	v_mov_b32_e32 v86, v36
	v_mov_b32_e32 v30, v37
	s_waitcnt vmcnt(4)
	v_lshlrev_b32_e32 v46, 16, v184
	v_and_b32_e32 v47, 0xffff0000, v184
	v_lshlrev_b32_e32 v32, 16, v185
	v_and_b32_e32 v33, 0xffff0000, v185
	s_waitcnt vmcnt(3)
	v_lshlrev_b32_e32 v48, 16, v186
	v_and_b32_e32 v49, 0xffff0000, v186
	v_lshlrev_b32_e32 v34, 16, v187
	v_and_b32_e32 v35, 0xffff0000, v187
	v_pk_add_f32 v[46:47], v[46:47], v[48:49]
	v_pk_add_f32 v[32:33], v[32:33], v[34:35]
	s_waitcnt vmcnt(2)
	v_lshlrev_b32_e32 v34, 16, v188
	v_and_b32_e32 v35, 0xffff0000, v188
	v_lshlrev_b32_e32 v42, 16, v189
	v_and_b32_e32 v43, 0xffff0000, v189
	s_waitcnt vmcnt(1)
	v_lshlrev_b32_e32 v48, 16, v190
	v_and_b32_e32 v49, 0xffff0000, v190
	v_lshlrev_b32_e32 v40, 16, v191
	v_and_b32_e32 v41, 0xffff0000, v191
	v_pk_add_f32 v[34:35], v[34:35], v[48:49]
	v_pk_add_f32 v[40:41], v[42:43], v[40:41]
	v_pk_add_f32 v[42:43], v[46:47], v[34:35]
	v_pk_add_f32 v[40:41], v[32:33], v[40:41]
	s_nop 0
	v_mov_b32_e32 v49, v28
	v_mov_b32_e32 v48, v38
	v_mov_b32_e32 v28, v39
	s_waitcnt vmcnt(0)
	v_pk_mul_f32 v[32:33], v[132:133], v[42:43]
	v_pk_mul_f32 v[34:35], v[134:135], v[40:41]
	v_pk_fma_f32 v[4:5], v[4:5], s[38:39], v[32:33] op_sel_hi:[1,0,1]
	v_pk_fma_f32 v[6:7], v[6:7], s[38:39], v[34:35] op_sel_hi:[1,0,1]
	s_branch .LBB0_1159

;     ...
;         if (POST) {
;             float s = 0.f;
; #pragma unroll
;             for (int j = 0; j < 8; ++j) s += (v[j].x + v[j].y) + (v[j].z + v[j].w);
;             const float mean = wave_sum(s) * (1.f / D); float s2 = 0.f;
; #pragma unroll
;             for (int j = 0; j < 8; ++j) { v[j] = v[j] - mean; s2 += (v[j].x * v[j].x + v[j].y * v[j].y) + (v[j].z * v[j].z + v[j].w * v[j].w); }
;             const float rstd = 1.f / sqrtf(wave_sum(s2) * (1.f / D) + LN_EPS);
; #pragma unroll
;             for (int j = 0; j < 8; ++j) { const f32x4 gg = ((const f32x4*)g)[F.lane + 64 * j], bb = ((const f32x4*)b)[F.lane + 64 * j]; v[j] = v[j] * rstd * gg + bb; if (WX || m >= ML) ((f32x4*)xr)[F.lane + 64 * j] = v[j]; }
.LBB0_1159:
	v_pk_add_f32 v[36:37], v[48:49], v[28:29]
	v_pk_add_f32 v[38:39], v[86:87], v[30:31]
	v_mov_b32_e32 v50, v25
	v_pk_add_f32 v[36:37], v[36:37], v[38:39]
	v_mov_b32_e32 v51, v26
	v_mov_b32_e32 v25, v27
	v_add_f32_e32 v3, 0, v37
	v_add_f32_e32 v43, v36, v3
	v_pk_add_f32 v[36:37], v[50:51], v[24:25]
	v_mov_b32_e32 v46, v17
	v_pk_add_f32 v[36:37], v[36:37], v[36:37] op_sel_hi:[0,1]
	v_mov_b32_e32 v42, v19
	v_add_f32_e32 v17, v20, v21
	v_add_f32_e32 v47, v22, v23
	v_mov_b32_e32 v19, v37
	v_mov_b32_e32 v40, v13
	v_mov_b32_e32 v41, v14
	v_mov_b32_e32 v13, v15
	v_pk_add_f32 v[38:39], v[16:17], v[46:47]
	v_pk_add_f32 v[36:37], v[18:19], v[42:43]
	v_mov_b32_e32 v32, v4
	v_pk_add_f32 v[36:37], v[38:39], v[36:37]
	v_pk_add_f32 v[38:39], v[40:41], v[12:13]
	v_pk_add_f32 v[36:37], v[36:37], v[36:37] op_sel_hi:[0,1]
	v_pk_add_f32 v[38:39], v[38:39], v[38:39] op_sel_hi:[0,1]
	v_mov_b32_e32 v34, v5
	v_mov_b32_e32 v14, v6
	v_mov_b32_e32 v26, v7
	v_add_f32_e32 v33, v8, v9
	v_add_f32_e32 v35, v10, v11
	v_mov_b32_e32 v15, v39
	v_mov_b32_e32 v27, v37
	v_pk_add_f32 v[32:33], v[32:33], v[34:35]
	v_pk_add_f32 v[14:15], v[14:15], v[26:27]
	s_nop 0
	v_pk_add_f32 v[14:15], v[32:33], v[14:15]
	global_load_dwordx4 v[32:35], v[52:53], off
	global_load_dwordx4 v[36:39], v[54:55], off
	global_load_dwordx4 v[160:163], v[52:53], off offset:1024
	global_load_dwordx4 v[164:167], v[54:55], off offset:1024
	global_load_dwordx4 v[168:171], v[52:53], off offset:2048
	global_load_dwordx4 v[172:175], v[54:55], off offset:2048
	global_load_dwordx4 v[176:179], v[52:53], off offset:3072
	global_load_dwordx4 v[180:183], v[54:55], off offset:3072
	global_load_dwordx4 v[184:187], v[56:57], off
	global_load_dwordx4 v[188:191], v[58:59], off
	global_load_dwordx4 v[196:199], v[60:61], off
	global_load_dwordx4 v[200:203], v[62:63], off
	global_load_dwordx4 v[204:207], v[64:65], off
	global_load_dwordx4 v[208:211], v[66:67], off
	global_load_dwordx4 v[212:215], v[68:69], off
	global_load_dwordx4 v[216:219], v[70:71], off
	v_add_f32_e32 v3, v14, v15
	v_mov_b32_e32 v14, v2
	s_nop 0
	v_add_f32_dpp v3, v3, v3 quad_perm:[1,0,3,2] row_mask:0xf bank_mask:0xf bound_ctrl:1
	s_nop 1
	v_add_f32_dpp v3, v3, v3 quad_perm:[2,3,0,1] row_mask:0xf bank_mask:0xf bound_ctrl:1
	s_nop 1
	v_add_f32_dpp v3, v3, v3 row_half_mirror row_mask:0xf bank_mask:0xf bound_ctrl:1
	s_nop 1
	v_add_f32_dpp v3, v3, v3 row_mirror row_mask:0xf bank_mask:0xf bound_ctrl:1
	s_nop 1
	v_mov_b32_dpp v14, v3 row_bcast:15 row_mask:0xa bank_mask:0xf
	v_add_f32_e32 v3, v3, v14
	v_mov_b32_e32 v14, v2
	s_nop 1
	v_mov_b32_dpp v14, v3 row_bcast:31 row_mask:0xc bank_mask:0xf
	v_add_f32_e32 v3, v3, v14
	s_nop 0
	v_readlane_b32 s11, v3, 63
	s_nop 1
	v_fmac_f32_e32 v31, s11, v224
	v_fmac_f32_e32 v29, s11, v224
	v_fmac_f32_e32 v87, s11, v224
	v_fmac_f32_e32 v49, s11, v224
	v_mul_f32_e32 v3, v29, v29
	v_mul_f32_e32 v14, v31, v31
	v_fmac_f32_e32 v3, v49, v49
	v_fmac_f32_e32 v14, v87, v87
	v_fmac_f32_e32 v30, s11, v224
	v_fmac_f32_e32 v28, s11, v224
	v_add_f32_e32 v3, v3, v14
	v_fmac_f32_e32 v86, s11, v224
	v_fmac_f32_e32 v48, s11, v224
	v_mul_f32_e32 v14, v28, v28
	v_mul_f32_e32 v15, v30, v30
	v_fmac_f32_e32 v14, v48, v48
	v_fmac_f32_e32 v15, v86, v86
	v_add_f32_e32 v14, v14, v15
	v_fmac_f32_e32 v25, s11, v224
	v_fmac_f32_e32 v50, s11, v224
	v_add_f32_e32 v3, v3, v14
	v_fmac_f32_e32 v51, s11, v224
	v_fmac_f32_e32 v24, s11, v224
	v_mul_f32_e32 v14, v50, v50
	v_mul_f32_e32 v15, v25, v25
	v_fmac_f32_e32 v14, v24, v24
	v_fmac_f32_e32 v15, v51, v51
	v_add_f32_e32 v14, v14, v15
	v_fmac_f32_e32 v23, s11, v224
	v_fmac_f32_e32 v21, s11, v224
	v_add_f32_e32 v3, v14, v3
	v_fmac_f32_e32 v22, s11, v224
	v_fmac_f32_e32 v20, s11, v224
	v_mul_f32_e32 v14, v21, v21
	v_mul_f32_e32 v15, v23, v23
	v_fmac_f32_e32 v14, v20, v20
	v_fmac_f32_e32 v15, v22, v22
	v_add_f32_e32 v14, v14, v15
	v_fmac_f32_e32 v42, s11, v224
	v_fmac_f32_e32 v46, s11, v224
	v_add_f32_e32 v3, v14, v3
	v_fmac_f32_e32 v18, s11, v224
	v_fmac_f32_e32 v16, s11, v224
	v_mul_f32_e32 v14, v46, v46
	v_mul_f32_e32 v15, v42, v42
	v_fmac_f32_e32 v14, v16, v16
	v_fmac_f32_e32 v15, v18, v18
	v_add_f32_e32 v14, v14, v15
	v_fmac_f32_e32 v13, s11, v224
	v_fmac_f32_e32 v40, s11, v224
	v_add_f32_e32 v3, v14, v3
	v_fmac_f32_e32 v41, s11, v224
	v_fmac_f32_e32 v12, s11, v224
	v_mul_f32_e32 v14, v40, v40
	v_mul_f32_e32 v15, v13, v13
	v_fmac_f32_e32 v14, v12, v12
	v_fmac_f32_e32 v15, v41, v41
	v_add_f32_e32 v14, v14, v15
	v_fmac_f32_e32 v11, s11, v224
	v_fmac_f32_e32 v9, s11, v224
	v_add_f32_e32 v3, v14, v3
	v_fmac_f32_e32 v10, s11, v224
	v_fmac_f32_e32 v8, s11, v224
	v_mul_f32_e32 v14, v9, v9
	v_mul_f32_e32 v15, v11, v11
	v_fma_f32 v89, s11, v224, v7
	v_fma_f32 v5, s11, v224, v5
	v_fmac_f32_e32 v14, v8, v8
	v_fmac_f32_e32 v15, v10, v10
	v_fma_f32 v88, s11, v224, v6
	v_fmac_f32_e32 v4, s11, v224
	v_mul_f32_e32 v6, v5, v5
	v_mul_f32_e32 v7, v89, v89
	v_add_f32_e32 v14, v14, v15
	v_fmac_f32_e32 v6, v4, v4
	v_fmac_f32_e32 v7, v88, v88
	v_add_f32_e32 v3, v14, v3
	v_add_f32_e32 v6, v6, v7
	v_add_f32_e32 v3, v6, v3
	v_mov_b32_e32 v6, v2
	s_nop 0
	v_add_f32_dpp v3, v3, v3 quad_perm:[1,0,3,2] row_mask:0xf bank_mask:0xf bound_ctrl:1
	s_nop 1
	v_add_f32_dpp v3, v3, v3 quad_perm:[2,3,0,1] row_mask:0xf bank_mask:0xf bound_ctrl:1
	s_nop 1
	v_add_f32_dpp v3, v3, v3 row_half_mirror row_mask:0xf bank_mask:0xf bound_ctrl:1
	s_nop 1
	v_add_f32_dpp v3, v3, v3 row_mirror row_mask:0xf bank_mask:0xf bound_ctrl:1
	s_nop 1
	v_mov_b32_dpp v6, v3 row_bcast:15 row_mask:0xa bank_mask:0xf
	v_add_f32_e32 v3, v3, v6
	v_mov_b32_e32 v6, v2
	s_nop 1
	v_mov_b32_dpp v6, v3 row_bcast:31 row_mask:0xc bank_mask:0xf
	v_add_f32_e32 v3, v3, v6
	s_nop 0
	v_readlane_b32 s4, v3, 63
	s_nop 1
	v_fma_f32 v3, s4, v226, v225
	v_cmp_gt_f32_e32 vcc, s64, v3
	v_mul_f32_e32 v6, 0x4f800000, v3
	s_nop 0
	v_cndmask_b32_e32 v3, v3, v6, vcc
	v_sqrt_f32_e32 v6, v3
	s_nop 0
	v_add_u32_e32 v7, -1, v6
	v_fma_f32 v14, -v7, v6, v3
	v_cmp_ge_f32_e64 s[4:5], 0, v14
	v_add_u32_e32 v14, 1, v6
	s_nop 0
	v_cndmask_b32_e64 v7, v6, v7, s[4:5]
	v_fma_f32 v6, -v14, v6, v3
	v_cmp_lt_f32_e64 s[4:5], 0, v6
	s_nop 1
	v_cndmask_b32_e64 v6, v7, v14, s[4:5]
	v_mul_f32_e32 v7, 0x37800000, v6
	v_cndmask_b32_e32 v6, v6, v7, vcc
	v_cmp_class_f32_e32 vcc, v3, v227
	s_nop 1
	v_cndmask_b32_e32 v3, v6, v3, vcc
	v_div_scale_f32 v6, s[4:5], v3, v3, 1.0
	v_rcp_f32_e32 v7, v6
	s_nop 0
	v_fma_f32 v14, -v6, v7, 1.0
	v_fmac_f32_e32 v7, v14, v7
	v_div_scale_f32 v14, vcc, 1.0, v3, 1.0
	v_mul_f32_e32 v15, v14, v7
	v_fma_f32 v17, -v6, v15, v14
	v_fmac_f32_e32 v15, v17, v7
	v_fma_f32 v6, -v6, v15, v14
	v_div_fmas_f32 v6, v6, v7, v15
	v_div_fixup_f32 v90, v6, v3, 1.0
	v_mov_b32_e32 v6, v49
	v_mov_b32_e32 v7, v29
	v_mov_b32_e32 v14, v87
	v_mov_b32_e32 v15, v31
	v_pk_mul_f32 v[6:7], v[6:7], v[90:91] op_sel_hi:[1,0]
	v_pk_mul_f32 v[14:15], v[14:15], v[90:91] op_sel_hi:[1,0]
	v_cndmask_b32_e64 v3, 0, 1, s[28:29]
	s_waitcnt vmcnt(0)
;     ...
; #pragma unroll
;             for (int j = 0; j < 8; ++j) { const f32x4 gg = ((const f32x4*)g)[F.lane + 64 * j], bb = ((const f32x4*)b)[F.lane + 64 * j]; v[j] = v[j] * rstd * gg + bb; if (WX || m >= ML) ((f32x4*)xr)[F.lane + 64 * j] = v[j]; }
	v_pk_fma_f32 v[34:35], v[34:35], v[14:15], v[38:39]
	v_pk_fma_f32 v[32:33], v[32:33], v[6:7], v[36:37]
	v_cmp_ne_u32_e64 s[4:5], 1, v3
	s_andn2_b64 vcc, exec, s[28:29]
	s_cbranch_vccnz .LBB0_1161
	global_store_dwordx4 v[44:45], v[32:35], off
.LBB0_1161:
	s_nop 0
	s_nop 0
	v_mov_b32_e32 v49, v28
	v_mov_b32_e32 v91, v90
	v_mov_b32_e32 v6, v90
	v_mov_b32_e32 v7, v90
	v_mov_b32_e32 v87, v30
	v_pk_mul_f32 v[14:15], v[86:87], v[6:7]
	v_pk_mul_f32 v[26:27], v[48:49], v[90:91]
	s_and_b64 vcc, exec, s[4:5]
	s_nop 0
	v_pk_fma_f32 v[28:29], v[14:15], v[162:163], v[166:167]
	v_pk_fma_f32 v[26:27], v[26:27], v[160:161], v[164:165]
	s_cbranch_vccnz .LBB0_1163
	global_store_dwordx4 v[44:45], v[26:29], off offset:1024
.LBB0_1163:
	s_nop 0
	s_nop 0
	v_mov_b32_e32 v14, v24
	v_mov_b32_e32 v15, v50
	v_mov_b32_e32 v24, v51
	v_pk_mul_f32 v[6:7], v[24:25], v[6:7]
	v_pk_mul_f32 v[14:15], v[14:15], v[90:91]
	s_and_b64 vcc, exec, s[4:5]
	s_nop 0
	v_pk_fma_f32 v[38:39], v[6:7], v[170:171], v[174:175]
	v_pk_fma_f32 v[36:37], v[14:15], v[168:169], v[172:173]
	s_cbranch_vccnz .LBB0_1165
	global_store_dwordx4 v[44:45], v[36:39], off offset:2048
.LBB0_1165:
	s_nop 0
	s_nop 0
	v_mov_b32_e32 v6, v90
	v_mov_b32_e32 v7, v90
	v_pk_mul_f32 v[14:15], v[20:21], v[90:91]
	v_pk_mul_f32 v[20:21], v[22:23], v[6:7]
	s_and_b64 vcc, exec, s[4:5]
	s_nop 0
	v_pk_fma_f32 v[22:23], v[20:21], v[178:179], v[182:183]
	v_pk_fma_f32 v[20:21], v[14:15], v[176:177], v[180:181]
	s_cbranch_vccnz .LBB0_1167
	global_store_dwordx4 v[44:45], v[20:23], off offset:3072
.LBB0_1167:
	v_mov_b32_e32 v17, v46
	s_nop 0
	s_nop 0
	v_mov_b32_e32 v19, v42
	v_pk_mul_f32 v[6:7], v[18:19], v[6:7]
	v_pk_mul_f32 v[14:15], v[16:17], v[90:91]
	s_and_b64 vcc, exec, s[4:5]
	s_nop 0
	v_pk_fma_f32 v[16:17], v[6:7], v[186:187], v[190:191]
	v_pk_fma_f32 v[14:15], v[14:15], v[184:185], v[188:189]
	s_cbranch_vccnz .LBB0_1169
	s_mov_b64 s[28:29], 0x1000
	v_lshl_add_u64 v[6:7], v[44:45], 0, s[28:29]
	global_store_dwordx4 v[6:7], v[14:17], off
.LBB0_1169:
	s_nop 0
	s_nop 0
	v_mov_b32_e32 v18, v12
	v_mov_b32_e32 v19, v40
	v_mov_b32_e32 v6, v90
	v_mov_b32_e32 v7, v90
	v_mov_b32_e32 v12, v41
	v_pk_mul_f32 v[12:13], v[12:13], v[6:7]
	v_pk_mul_f32 v[18:19], v[18:19], v[90:91]
	s_and_b64 vcc, exec, s[4:5]
	s_nop 0
	v_pk_fma_f32 v[42:43], v[12:13], v[198:199], v[202:203]
	v_pk_fma_f32 v[40:41], v[18:19], v[196:197], v[200:201]
	s_cbranch_vccnz .LBB0_1171
	s_mov_b64 s[28:29], 0x1400
	v_lshl_add_u64 v[12:13], v[44:45], 0, s[28:29]
	global_store_dwordx4 v[12:13], v[40:43], off
.LBB0_1171:
	s_nop 0
	s_nop 0
	v_pk_mul_f32 v[6:7], v[10:11], v[6:7]
	v_pk_mul_f32 v[10:11], v[8:9], v[90:91]
	s_and_b64 vcc, exec, s[4:5]
	s_nop 0
	v_pk_fma_f32 v[8:9], v[6:7], v[206:207], v[210:211]
	v_pk_fma_f32 v[6:7], v[10:11], v[204:205], v[208:209]
	s_cbranch_vccnz .LBB0_1173
	s_mov_b64 s[28:29], 0x1800
	v_lshl_add_u64 v[10:11], v[44:45], 0, s[28:29]
	global_store_dwordx4 v[10:11], v[6:9], off
.LBB0_1173:
	s_nop 0
	s_nop 0
	s_nop 0
	v_mov_b32_e32 v18, v90
	v_mov_b32_e32 v19, v90
	v_pk_mul_f32 v[4:5], v[4:5], v[90:91]
	v_pk_mul_f32 v[18:19], v[88:89], v[18:19]
	s_and_b64 vcc, exec, s[4:5]
	s_nop 0
	v_pk_fma_f32 v[12:13], v[18:19], v[214:215], v[218:219]
	v_pk_fma_f32 v[10:11], v[4:5], v[212:213], v[216:217]
	s_cbranch_vccnz .LBB0_1175
	s_mov_b64 s[4:5], 0x1c00
	v_lshl_add_u64 v[4:5], v[44:45], 0, s[4:5]
	global_store_dwordx4 v[4:5], v[10:13], off
